# OUT and DOWN residual epilogues replaced by hand-written lean version (scalar bases, one gate load per block, all 8 residual loads hoisted per section, counted waits)
# baseline (speedup 1.0000x reference)
.Lg16_out_k:
	s_add_i32 s9, s3, 2
	s_lshl_b32 s96, s9, 13
	s_add_i32 m0, vcc_lo, 16384
	v_lshl_add_u64 v[160:161], v[188:189], 0, s[96:97]
	global_load_lds_dwordx4 v[160:161], off
	global_load_lds_dwordx4 v[160:161], off offset:1024
	ds_read_b128 v[196:199], v246 offset:0
	ds_read_b128 v[200:203], v246 offset:1024
	ds_read_b128 v[204:207], v246 offset:2048
	ds_read_b128 v[242:245], v246 offset:3072
	s_add_i32 s9, s3, 2
	s_lshl_b32 s96, s9, 11
	v_lshl_add_u64 v[248:249], v[184:185], 0, s[96:97]
	v_lshl_add_u64 v[250:251], v[186:187], 0, s[96:97]
	s_waitcnt vmcnt(8) lgkmcnt(3)
	v_mfma_f32_16x16x32_bf16 v[112:115], v[128:131], v[196:199], v[112:115]
	v_mfma_f32_16x16x32_bf16 v[120:123], v[132:135], v[196:199], v[120:123]
	v_mfma_f32_16x16x32_bf16 v[48:51], v[136:139], v[196:199], v[48:51]
	v_mfma_f32_16x16x32_bf16 v[56:59], v[140:143], v[196:199], v[56:59]
	ds_read_b128 v[196:199], v246 offset:4096
	s_waitcnt lgkmcnt(3)
	v_mfma_f32_16x16x32_bf16 v[116:119], v[128:131], v[200:203], v[116:119]
	v_mfma_f32_16x16x32_bf16 v[124:127], v[132:135], v[200:203], v[124:127]
	v_mfma_f32_16x16x32_bf16 v[52:55], v[136:139], v[200:203], v[52:55]
	v_mfma_f32_16x16x32_bf16 v[60:63], v[140:143], v[200:203], v[60:63]
	ds_read_b128 v[200:203], v246 offset:5120
	s_waitcnt lgkmcnt(3)
	v_mfma_f32_16x16x32_bf16 v[96:99], v[128:131], v[204:207], v[96:99]
	v_mfma_f32_16x16x32_bf16 v[104:107], v[132:135], v[204:207], v[104:107]
	v_mfma_f32_16x16x32_bf16 v[32:35], v[136:139], v[204:207], v[32:35]
	v_mfma_f32_16x16x32_bf16 v[40:43], v[140:143], v[204:207], v[40:43]
	ds_read_b128 v[204:207], v246 offset:6144
	s_waitcnt lgkmcnt(3)
	v_mfma_f32_16x16x32_bf16 v[100:103], v[128:131], v[242:245], v[100:103]
	v_mfma_f32_16x16x32_bf16 v[108:111], v[132:135], v[242:245], v[108:111]
	v_mfma_f32_16x16x32_bf16 v[36:39], v[136:139], v[242:245], v[36:39]
	v_mfma_f32_16x16x32_bf16 v[44:47], v[140:143], v[242:245], v[44:47]
	ds_read_b128 v[242:245], v246 offset:7168
	s_waitcnt lgkmcnt(3)
	v_mfma_f32_16x16x32_bf16 v[80:83], v[128:131], v[196:199], v[80:83]
	v_mfma_f32_16x16x32_bf16 v[88:91], v[132:135], v[196:199], v[88:91]
	v_mfma_f32_16x16x32_bf16 v[16:19], v[136:139], v[196:199], v[16:19]
	v_mfma_f32_16x16x32_bf16 v[24:27], v[140:143], v[196:199], v[24:27]
	s_waitcnt lgkmcnt(2)
	v_mfma_f32_16x16x32_bf16 v[84:87], v[128:131], v[200:203], v[84:87]
	v_mfma_f32_16x16x32_bf16 v[92:95], v[132:135], v[200:203], v[92:95]
	v_mfma_f32_16x16x32_bf16 v[20:23], v[136:139], v[200:203], v[20:23]
	v_mfma_f32_16x16x32_bf16 v[28:31], v[140:143], v[200:203], v[28:31]
	s_waitcnt lgkmcnt(1)
	v_mfma_f32_16x16x32_bf16 v[64:67], v[128:131], v[204:207], v[64:67]
	v_mfma_f32_16x16x32_bf16 v[72:75], v[132:135], v[204:207], v[72:75]
	v_mfma_f32_16x16x32_bf16 v[0:3], v[136:139], v[204:207], v[0:3]
	v_mfma_f32_16x16x32_bf16 v[8:11], v[140:143], v[204:207], v[8:11]
	s_waitcnt lgkmcnt(0)
	v_mfma_f32_16x16x32_bf16 v[68:71], v[128:131], v[242:245], v[68:71]
	v_mfma_f32_16x16x32_bf16 v[76:79], v[132:135], v[242:245], v[76:79]
	v_mfma_f32_16x16x32_bf16 v[4:7], v[136:139], v[242:245], v[4:7]
	v_mfma_f32_16x16x32_bf16 v[12:15], v[140:143], v[242:245], v[12:15]
	global_load_dwordx4 v[128:131], v[248:249], off
	global_load_dwordx4 v[132:135], v[248:249], off offset:256
	global_load_dwordx4 v[136:139], v[250:251], off
	global_load_dwordx4 v[140:143], v[250:251], off offset:256
	s_waitcnt vmcnt(10)
	s_barrier
	s_add_i32 s9, s3, 3
	s_lshl_b32 s96, s9, 13
	s_mov_b32 m0, vcc_lo
	v_lshl_add_u64 v[160:161], v[188:189], 0, s[96:97]
	global_load_lds_dwordx4 v[160:161], off
	global_load_lds_dwordx4 v[160:161], off offset:1024
	ds_read_b128 v[196:199], v246 offset:8192
	ds_read_b128 v[200:203], v246 offset:9216
	ds_read_b128 v[204:207], v246 offset:10240
	ds_read_b128 v[242:245], v246 offset:11264
	s_add_i32 s9, s3, 3
	s_lshl_b32 s96, s9, 11
	v_lshl_add_u64 v[248:249], v[184:185], 0, s[96:97]
	v_lshl_add_u64 v[250:251], v[186:187], 0, s[96:97]
	s_waitcnt vmcnt(8) lgkmcnt(3)
	v_mfma_f32_16x16x32_bf16 v[112:115], v[144:147], v[196:199], v[112:115]
	v_mfma_f32_16x16x32_bf16 v[120:123], v[148:151], v[196:199], v[120:123]
	v_mfma_f32_16x16x32_bf16 v[48:51], v[152:155], v[196:199], v[48:51]
	v_mfma_f32_16x16x32_bf16 v[56:59], v[156:159], v[196:199], v[56:59]
	ds_read_b128 v[196:199], v246 offset:12288
	s_waitcnt lgkmcnt(3)
	v_mfma_f32_16x16x32_bf16 v[116:119], v[144:147], v[200:203], v[116:119]
	v_mfma_f32_16x16x32_bf16 v[124:127], v[148:151], v[200:203], v[124:127]
	v_mfma_f32_16x16x32_bf16 v[52:55], v[152:155], v[200:203], v[52:55]
	v_mfma_f32_16x16x32_bf16 v[60:63], v[156:159], v[200:203], v[60:63]
	ds_read_b128 v[200:203], v246 offset:13312
	s_waitcnt lgkmcnt(3)
	v_mfma_f32_16x16x32_bf16 v[96:99], v[144:147], v[204:207], v[96:99]
	v_mfma_f32_16x16x32_bf16 v[104:107], v[148:151], v[204:207], v[104:107]
	v_mfma_f32_16x16x32_bf16 v[32:35], v[152:155], v[204:207], v[32:35]
	v_mfma_f32_16x16x32_bf16 v[40:43], v[156:159], v[204:207], v[40:43]
	ds_read_b128 v[204:207], v246 offset:14336
	s_waitcnt lgkmcnt(3)
	v_mfma_f32_16x16x32_bf16 v[100:103], v[144:147], v[242:245], v[100:103]
	v_mfma_f32_16x16x32_bf16 v[108:111], v[148:151], v[242:245], v[108:111]
	v_mfma_f32_16x16x32_bf16 v[36:39], v[152:155], v[242:245], v[36:39]
	v_mfma_f32_16x16x32_bf16 v[44:47], v[156:159], v[242:245], v[44:47]
	ds_read_b128 v[242:245], v246 offset:15360
	s_waitcnt lgkmcnt(3)
	v_mfma_f32_16x16x32_bf16 v[80:83], v[144:147], v[196:199], v[80:83]
	v_mfma_f32_16x16x32_bf16 v[88:91], v[148:151], v[196:199], v[88:91]
	v_mfma_f32_16x16x32_bf16 v[16:19], v[152:155], v[196:199], v[16:19]
	v_mfma_f32_16x16x32_bf16 v[24:27], v[156:159], v[196:199], v[24:27]
	s_waitcnt lgkmcnt(2)
	v_mfma_f32_16x16x32_bf16 v[84:87], v[144:147], v[200:203], v[84:87]
	v_mfma_f32_16x16x32_bf16 v[92:95], v[148:151], v[200:203], v[92:95]
	v_mfma_f32_16x16x32_bf16 v[20:23], v[152:155], v[200:203], v[20:23]
	v_mfma_f32_16x16x32_bf16 v[28:31], v[156:159], v[200:203], v[28:31]
	s_waitcnt lgkmcnt(1)
	v_mfma_f32_16x16x32_bf16 v[64:67], v[144:147], v[204:207], v[64:67]
	v_mfma_f32_16x16x32_bf16 v[72:75], v[148:151], v[204:207], v[72:75]
	v_mfma_f32_16x16x32_bf16 v[0:3], v[152:155], v[204:207], v[0:3]
	v_mfma_f32_16x16x32_bf16 v[8:11], v[156:159], v[204:207], v[8:11]
	s_waitcnt lgkmcnt(0)
	v_mfma_f32_16x16x32_bf16 v[68:71], v[144:147], v[242:245], v[68:71]
	v_mfma_f32_16x16x32_bf16 v[76:79], v[148:151], v[242:245], v[76:79]
	v_mfma_f32_16x16x32_bf16 v[4:7], v[152:155], v[242:245], v[4:7]
	v_mfma_f32_16x16x32_bf16 v[12:15], v[156:159], v[242:245], v[12:15]
	global_load_dwordx4 v[144:147], v[248:249], off
	global_load_dwordx4 v[148:151], v[248:249], off offset:256
	global_load_dwordx4 v[152:155], v[250:251], off
	global_load_dwordx4 v[156:159], v[250:251], off offset:256
	s_waitcnt vmcnt(10)
	s_barrier
	s_add_i32 s9, s3, 4
	s_lshl_b32 s96, s9, 13
	s_add_i32 m0, vcc_lo, 8192
	v_lshl_add_u64 v[160:161], v[188:189], 0, s[96:97]
	global_load_lds_dwordx4 v[160:161], off
	global_load_lds_dwordx4 v[160:161], off offset:1024
	ds_read_b128 v[196:199], v246 offset:16384
	ds_read_b128 v[200:203], v246 offset:17408
	ds_read_b128 v[204:207], v246 offset:18432
	ds_read_b128 v[242:245], v246 offset:19456
	s_add_i32 s9, s3, 4
	s_lshl_b32 s96, s9, 11
	v_lshl_add_u64 v[248:249], v[184:185], 0, s[96:97]
	v_lshl_add_u64 v[250:251], v[186:187], 0, s[96:97]
	s_waitcnt vmcnt(8) lgkmcnt(3)
	v_mfma_f32_16x16x32_bf16 v[112:115], v[128:131], v[196:199], v[112:115]
	v_mfma_f32_16x16x32_bf16 v[120:123], v[132:135], v[196:199], v[120:123]
	v_mfma_f32_16x16x32_bf16 v[48:51], v[136:139], v[196:199], v[48:51]
	v_mfma_f32_16x16x32_bf16 v[56:59], v[140:143], v[196:199], v[56:59]
	ds_read_b128 v[196:199], v246 offset:20480
	s_waitcnt lgkmcnt(3)
	v_mfma_f32_16x16x32_bf16 v[116:119], v[128:131], v[200:203], v[116:119]
	v_mfma_f32_16x16x32_bf16 v[124:127], v[132:135], v[200:203], v[124:127]
	v_mfma_f32_16x16x32_bf16 v[52:55], v[136:139], v[200:203], v[52:55]
	v_mfma_f32_16x16x32_bf16 v[60:63], v[140:143], v[200:203], v[60:63]
	ds_read_b128 v[200:203], v246 offset:21504
	s_waitcnt lgkmcnt(3)
	v_mfma_f32_16x16x32_bf16 v[96:99], v[128:131], v[204:207], v[96:99]
	v_mfma_f32_16x16x32_bf16 v[104:107], v[132:135], v[204:207], v[104:107]
	v_mfma_f32_16x16x32_bf16 v[32:35], v[136:139], v[204:207], v[32:35]
	v_mfma_f32_16x16x32_bf16 v[40:43], v[140:143], v[204:207], v[40:43]
	ds_read_b128 v[204:207], v246 offset:22528
	s_waitcnt lgkmcnt(3)
	v_mfma_f32_16x16x32_bf16 v[100:103], v[128:131], v[242:245], v[100:103]
	v_mfma_f32_16x16x32_bf16 v[108:111], v[132:135], v[242:245], v[108:111]
	v_mfma_f32_16x16x32_bf16 v[36:39], v[136:139], v[242:245], v[36:39]
	v_mfma_f32_16x16x32_bf16 v[44:47], v[140:143], v[242:245], v[44:47]
	ds_read_b128 v[242:245], v246 offset:23552
	s_waitcnt lgkmcnt(3)
	v_mfma_f32_16x16x32_bf16 v[80:83], v[128:131], v[196:199], v[80:83]
	v_mfma_f32_16x16x32_bf16 v[88:91], v[132:135], v[196:199], v[88:91]
	v_mfma_f32_16x16x32_bf16 v[16:19], v[136:139], v[196:199], v[16:19]
	v_mfma_f32_16x16x32_bf16 v[24:27], v[140:143], v[196:199], v[24:27]
	s_waitcnt lgkmcnt(2)
	v_mfma_f32_16x16x32_bf16 v[84:87], v[128:131], v[200:203], v[84:87]
	v_mfma_f32_16x16x32_bf16 v[92:95], v[132:135], v[200:203], v[92:95]
	v_mfma_f32_16x16x32_bf16 v[20:23], v[136:139], v[200:203], v[20:23]
	v_mfma_f32_16x16x32_bf16 v[28:31], v[140:143], v[200:203], v[28:31]
	s_waitcnt lgkmcnt(1)
	v_mfma_f32_16x16x32_bf16 v[64:67], v[128:131], v[204:207], v[64:67]
	v_mfma_f32_16x16x32_bf16 v[72:75], v[132:135], v[204:207], v[72:75]
	v_mfma_f32_16x16x32_bf16 v[0:3], v[136:139], v[204:207], v[0:3]
	v_mfma_f32_16x16x32_bf16 v[8:11], v[140:143], v[204:207], v[8:11]
	s_waitcnt lgkmcnt(0)
	v_mfma_f32_16x16x32_bf16 v[68:71], v[128:131], v[242:245], v[68:71]
	v_mfma_f32_16x16x32_bf16 v[76:79], v[132:135], v[242:245], v[76:79]
	v_mfma_f32_16x16x32_bf16 v[4:7], v[136:139], v[242:245], v[4:7]
	v_mfma_f32_16x16x32_bf16 v[12:15], v[140:143], v[242:245], v[12:15]
	global_load_dwordx4 v[128:131], v[248:249], off
	global_load_dwordx4 v[132:135], v[248:249], off offset:256
	global_load_dwordx4 v[136:139], v[250:251], off
	global_load_dwordx4 v[140:143], v[250:251], off offset:256
	s_waitcnt vmcnt(10)
	s_barrier
	s_add_i32 s9, s3, 5
	s_lshl_b32 s96, s9, 13
	s_add_i32 m0, vcc_lo, 16384
	v_lshl_add_u64 v[160:161], v[188:189], 0, s[96:97]
	global_load_lds_dwordx4 v[160:161], off
	global_load_lds_dwordx4 v[160:161], off offset:1024
	ds_read_b128 v[196:199], v246 offset:0
	ds_read_b128 v[200:203], v246 offset:1024
	ds_read_b128 v[204:207], v246 offset:2048
	ds_read_b128 v[242:245], v246 offset:3072
	s_add_i32 s9, s3, 5
	s_lshl_b32 s96, s9, 11
	v_lshl_add_u64 v[248:249], v[184:185], 0, s[96:97]
	v_lshl_add_u64 v[250:251], v[186:187], 0, s[96:97]
	s_waitcnt vmcnt(8) lgkmcnt(3)
	v_mfma_f32_16x16x32_bf16 v[112:115], v[144:147], v[196:199], v[112:115]
	v_mfma_f32_16x16x32_bf16 v[120:123], v[148:151], v[196:199], v[120:123]
	v_mfma_f32_16x16x32_bf16 v[48:51], v[152:155], v[196:199], v[48:51]
	v_mfma_f32_16x16x32_bf16 v[56:59], v[156:159], v[196:199], v[56:59]
	ds_read_b128 v[196:199], v246 offset:4096
	s_waitcnt lgkmcnt(3)
	v_mfma_f32_16x16x32_bf16 v[116:119], v[144:147], v[200:203], v[116:119]
	v_mfma_f32_16x16x32_bf16 v[124:127], v[148:151], v[200:203], v[124:127]
	v_mfma_f32_16x16x32_bf16 v[52:55], v[152:155], v[200:203], v[52:55]
	v_mfma_f32_16x16x32_bf16 v[60:63], v[156:159], v[200:203], v[60:63]
	ds_read_b128 v[200:203], v246 offset:5120
	s_waitcnt lgkmcnt(3)
	v_mfma_f32_16x16x32_bf16 v[96:99], v[144:147], v[204:207], v[96:99]
	v_mfma_f32_16x16x32_bf16 v[104:107], v[148:151], v[204:207], v[104:107]
	v_mfma_f32_16x16x32_bf16 v[32:35], v[152:155], v[204:207], v[32:35]
	v_mfma_f32_16x16x32_bf16 v[40:43], v[156:159], v[204:207], v[40:43]
	ds_read_b128 v[204:207], v246 offset:6144
	s_waitcnt lgkmcnt(3)
	v_mfma_f32_16x16x32_bf16 v[100:103], v[144:147], v[242:245], v[100:103]
	v_mfma_f32_16x16x32_bf16 v[108:111], v[148:151], v[242:245], v[108:111]
	v_mfma_f32_16x16x32_bf16 v[36:39], v[152:155], v[242:245], v[36:39]
	v_mfma_f32_16x16x32_bf16 v[44:47], v[156:159], v[242:245], v[44:47]
	ds_read_b128 v[242:245], v246 offset:7168
	s_waitcnt lgkmcnt(3)
	v_mfma_f32_16x16x32_bf16 v[80:83], v[144:147], v[196:199], v[80:83]
	v_mfma_f32_16x16x32_bf16 v[88:91], v[148:151], v[196:199], v[88:91]
	v_mfma_f32_16x16x32_bf16 v[16:19], v[152:155], v[196:199], v[16:19]
	v_mfma_f32_16x16x32_bf16 v[24:27], v[156:159], v[196:199], v[24:27]
	s_waitcnt lgkmcnt(2)
	v_mfma_f32_16x16x32_bf16 v[84:87], v[144:147], v[200:203], v[84:87]
	v_mfma_f32_16x16x32_bf16 v[92:95], v[148:151], v[200:203], v[92:95]
	v_mfma_f32_16x16x32_bf16 v[20:23], v[152:155], v[200:203], v[20:23]
	v_mfma_f32_16x16x32_bf16 v[28:31], v[156:159], v[200:203], v[28:31]
	s_waitcnt lgkmcnt(1)
	v_mfma_f32_16x16x32_bf16 v[64:67], v[144:147], v[204:207], v[64:67]
	v_mfma_f32_16x16x32_bf16 v[72:75], v[148:151], v[204:207], v[72:75]
	v_mfma_f32_16x16x32_bf16 v[0:3], v[152:155], v[204:207], v[0:3]
	v_mfma_f32_16x16x32_bf16 v[8:11], v[156:159], v[204:207], v[8:11]
	s_waitcnt lgkmcnt(0)
	v_mfma_f32_16x16x32_bf16 v[68:71], v[144:147], v[242:245], v[68:71]
	v_mfma_f32_16x16x32_bf16 v[76:79], v[148:151], v[242:245], v[76:79]
	v_mfma_f32_16x16x32_bf16 v[4:7], v[152:155], v[242:245], v[4:7]
	v_mfma_f32_16x16x32_bf16 v[12:15], v[156:159], v[242:245], v[12:15]
	global_load_dwordx4 v[144:147], v[248:249], off
	global_load_dwordx4 v[148:151], v[248:249], off offset:256
	global_load_dwordx4 v[152:155], v[250:251], off
	global_load_dwordx4 v[156:159], v[250:251], off offset:256
	s_waitcnt vmcnt(10)
	s_barrier
	s_add_i32 s9, s3, 6
	s_lshl_b32 s96, s9, 13
	s_mov_b32 m0, vcc_lo
	v_lshl_add_u64 v[160:161], v[188:189], 0, s[96:97]
	global_load_lds_dwordx4 v[160:161], off
	global_load_lds_dwordx4 v[160:161], off offset:1024
	ds_read_b128 v[196:199], v246 offset:8192
	ds_read_b128 v[200:203], v246 offset:9216
	ds_read_b128 v[204:207], v246 offset:10240
	ds_read_b128 v[242:245], v246 offset:11264
	s_add_i32 s9, s3, 6
	s_lshl_b32 s96, s9, 11
	v_lshl_add_u64 v[248:249], v[184:185], 0, s[96:97]
	v_lshl_add_u64 v[250:251], v[186:187], 0, s[96:97]
	s_waitcnt vmcnt(8) lgkmcnt(3)
	v_mfma_f32_16x16x32_bf16 v[112:115], v[128:131], v[196:199], v[112:115]
	v_mfma_f32_16x16x32_bf16 v[120:123], v[132:135], v[196:199], v[120:123]
	v_mfma_f32_16x16x32_bf16 v[48:51], v[136:139], v[196:199], v[48:51]
	v_mfma_f32_16x16x32_bf16 v[56:59], v[140:143], v[196:199], v[56:59]
	ds_read_b128 v[196:199], v246 offset:12288
	s_waitcnt lgkmcnt(3)
	v_mfma_f32_16x16x32_bf16 v[116:119], v[128:131], v[200:203], v[116:119]
	v_mfma_f32_16x16x32_bf16 v[124:127], v[132:135], v[200:203], v[124:127]
	v_mfma_f32_16x16x32_bf16 v[52:55], v[136:139], v[200:203], v[52:55]
	v_mfma_f32_16x16x32_bf16 v[60:63], v[140:143], v[200:203], v[60:63]
	ds_read_b128 v[200:203], v246 offset:13312
	s_waitcnt lgkmcnt(3)
	v_mfma_f32_16x16x32_bf16 v[96:99], v[128:131], v[204:207], v[96:99]
	v_mfma_f32_16x16x32_bf16 v[104:107], v[132:135], v[204:207], v[104:107]
	v_mfma_f32_16x16x32_bf16 v[32:35], v[136:139], v[204:207], v[32:35]
	v_mfma_f32_16x16x32_bf16 v[40:43], v[140:143], v[204:207], v[40:43]
	ds_read_b128 v[204:207], v246 offset:14336
	s_waitcnt lgkmcnt(3)
	v_mfma_f32_16x16x32_bf16 v[100:103], v[128:131], v[242:245], v[100:103]
	v_mfma_f32_16x16x32_bf16 v[108:111], v[132:135], v[242:245], v[108:111]
	v_mfma_f32_16x16x32_bf16 v[36:39], v[136:139], v[242:245], v[36:39]
	v_mfma_f32_16x16x32_bf16 v[44:47], v[140:143], v[242:245], v[44:47]
	ds_read_b128 v[242:245], v246 offset:15360
	s_waitcnt lgkmcnt(3)
	v_mfma_f32_16x16x32_bf16 v[80:83], v[128:131], v[196:199], v[80:83]
	v_mfma_f32_16x16x32_bf16 v[88:91], v[132:135], v[196:199], v[88:91]
	v_mfma_f32_16x16x32_bf16 v[16:19], v[136:139], v[196:199], v[16:19]
	v_mfma_f32_16x16x32_bf16 v[24:27], v[140:143], v[196:199], v[24:27]
	s_waitcnt lgkmcnt(2)
	v_mfma_f32_16x16x32_bf16 v[84:87], v[128:131], v[200:203], v[84:87]
	v_mfma_f32_16x16x32_bf16 v[92:95], v[132:135], v[200:203], v[92:95]
	v_mfma_f32_16x16x32_bf16 v[20:23], v[136:139], v[200:203], v[20:23]
	v_mfma_f32_16x16x32_bf16 v[28:31], v[140:143], v[200:203], v[28:31]
	s_waitcnt lgkmcnt(1)
	v_mfma_f32_16x16x32_bf16 v[64:67], v[128:131], v[204:207], v[64:67]
	v_mfma_f32_16x16x32_bf16 v[72:75], v[132:135], v[204:207], v[72:75]
	v_mfma_f32_16x16x32_bf16 v[0:3], v[136:139], v[204:207], v[0:3]
	v_mfma_f32_16x16x32_bf16 v[8:11], v[140:143], v[204:207], v[8:11]
	s_waitcnt lgkmcnt(0)
	v_mfma_f32_16x16x32_bf16 v[68:71], v[128:131], v[242:245], v[68:71]
	v_mfma_f32_16x16x32_bf16 v[76:79], v[132:135], v[242:245], v[76:79]
	v_mfma_f32_16x16x32_bf16 v[4:7], v[136:139], v[242:245], v[4:7]
	v_mfma_f32_16x16x32_bf16 v[12:15], v[140:143], v[242:245], v[12:15]
	global_load_dwordx4 v[128:131], v[248:249], off
	global_load_dwordx4 v[132:135], v[248:249], off offset:256
	global_load_dwordx4 v[136:139], v[250:251], off
	global_load_dwordx4 v[140:143], v[250:251], off offset:256
	s_waitcnt vmcnt(10)
	s_barrier
	s_add_i32 s9, s3, 7
	s_lshl_b32 s96, s9, 13
	s_add_i32 m0, vcc_lo, 8192
	v_lshl_add_u64 v[160:161], v[188:189], 0, s[96:97]
	global_load_lds_dwordx4 v[160:161], off
	global_load_lds_dwordx4 v[160:161], off offset:1024
	ds_read_b128 v[196:199], v246 offset:16384
	ds_read_b128 v[200:203], v246 offset:17408
	ds_read_b128 v[204:207], v246 offset:18432
	ds_read_b128 v[242:245], v246 offset:19456
	s_add_i32 s9, s3, 7
	s_lshl_b32 s96, s9, 11
	v_lshl_add_u64 v[248:249], v[184:185], 0, s[96:97]
	v_lshl_add_u64 v[250:251], v[186:187], 0, s[96:97]
	s_waitcnt vmcnt(8) lgkmcnt(3)
	v_mfma_f32_16x16x32_bf16 v[112:115], v[144:147], v[196:199], v[112:115]
	v_mfma_f32_16x16x32_bf16 v[120:123], v[148:151], v[196:199], v[120:123]
	v_mfma_f32_16x16x32_bf16 v[48:51], v[152:155], v[196:199], v[48:51]
	v_mfma_f32_16x16x32_bf16 v[56:59], v[156:159], v[196:199], v[56:59]
	ds_read_b128 v[196:199], v246 offset:20480
	s_waitcnt lgkmcnt(3)
	v_mfma_f32_16x16x32_bf16 v[116:119], v[144:147], v[200:203], v[116:119]
	v_mfma_f32_16x16x32_bf16 v[124:127], v[148:151], v[200:203], v[124:127]
	v_mfma_f32_16x16x32_bf16 v[52:55], v[152:155], v[200:203], v[52:55]
	v_mfma_f32_16x16x32_bf16 v[60:63], v[156:159], v[200:203], v[60:63]
	ds_read_b128 v[200:203], v246 offset:21504
	s_waitcnt lgkmcnt(3)
	v_mfma_f32_16x16x32_bf16 v[96:99], v[144:147], v[204:207], v[96:99]
	v_mfma_f32_16x16x32_bf16 v[104:107], v[148:151], v[204:207], v[104:107]
	v_mfma_f32_16x16x32_bf16 v[32:35], v[152:155], v[204:207], v[32:35]
	v_mfma_f32_16x16x32_bf16 v[40:43], v[156:159], v[204:207], v[40:43]
	ds_read_b128 v[204:207], v246 offset:22528
	s_waitcnt lgkmcnt(3)
	v_mfma_f32_16x16x32_bf16 v[100:103], v[144:147], v[242:245], v[100:103]
	v_mfma_f32_16x16x32_bf16 v[108:111], v[148:151], v[242:245], v[108:111]
	v_mfma_f32_16x16x32_bf16 v[36:39], v[152:155], v[242:245], v[36:39]
	v_mfma_f32_16x16x32_bf16 v[44:47], v[156:159], v[242:245], v[44:47]
	ds_read_b128 v[242:245], v246 offset:23552
	s_waitcnt lgkmcnt(3)
	v_mfma_f32_16x16x32_bf16 v[80:83], v[144:147], v[196:199], v[80:83]
	v_mfma_f32_16x16x32_bf16 v[88:91], v[148:151], v[196:199], v[88:91]
	v_mfma_f32_16x16x32_bf16 v[16:19], v[152:155], v[196:199], v[16:19]
	v_mfma_f32_16x16x32_bf16 v[24:27], v[156:159], v[196:199], v[24:27]
	s_waitcnt lgkmcnt(2)
	v_mfma_f32_16x16x32_bf16 v[84:87], v[144:147], v[200:203], v[84:87]
	v_mfma_f32_16x16x32_bf16 v[92:95], v[148:151], v[200:203], v[92:95]
	v_mfma_f32_16x16x32_bf16 v[20:23], v[152:155], v[200:203], v[20:23]
	v_mfma_f32_16x16x32_bf16 v[28:31], v[156:159], v[200:203], v[28:31]
	s_waitcnt lgkmcnt(1)
	v_mfma_f32_16x16x32_bf16 v[64:67], v[144:147], v[204:207], v[64:67]
	v_mfma_f32_16x16x32_bf16 v[72:75], v[148:151], v[204:207], v[72:75]
	v_mfma_f32_16x16x32_bf16 v[0:3], v[152:155], v[204:207], v[0:3]
	v_mfma_f32_16x16x32_bf16 v[8:11], v[156:159], v[204:207], v[8:11]
	s_waitcnt lgkmcnt(0)
	v_mfma_f32_16x16x32_bf16 v[68:71], v[144:147], v[242:245], v[68:71]
	v_mfma_f32_16x16x32_bf16 v[76:79], v[148:151], v[242:245], v[76:79]
	v_mfma_f32_16x16x32_bf16 v[4:7], v[152:155], v[242:245], v[4:7]
	v_mfma_f32_16x16x32_bf16 v[12:15], v[156:159], v[242:245], v[12:15]
	global_load_dwordx4 v[144:147], v[248:249], off
	global_load_dwordx4 v[148:151], v[248:249], off offset:256
	global_load_dwordx4 v[152:155], v[250:251], off
	global_load_dwordx4 v[156:159], v[250:251], off offset:256
	s_waitcnt vmcnt(10)
	s_barrier
	s_add_i32 s3, s3, 6
	s_cmp_lt_u32 s3, 30
	s_cbranch_scc1 .Lg16_out_k
	ds_read_b128 v[196:199], v246 offset:0
	ds_read_b128 v[200:203], v246 offset:1024
	ds_read_b128 v[204:207], v246 offset:2048
	ds_read_b128 v[242:245], v246 offset:3072
	s_waitcnt vmcnt(6) lgkmcnt(3)
	v_mfma_f32_16x16x32_bf16 v[112:115], v[128:131], v[196:199], v[112:115]
	v_mfma_f32_16x16x32_bf16 v[120:123], v[132:135], v[196:199], v[120:123]
	v_mfma_f32_16x16x32_bf16 v[48:51], v[136:139], v[196:199], v[48:51]
	v_mfma_f32_16x16x32_bf16 v[56:59], v[140:143], v[196:199], v[56:59]
	ds_read_b128 v[196:199], v246 offset:4096
	s_waitcnt lgkmcnt(3)
	v_mfma_f32_16x16x32_bf16 v[116:119], v[128:131], v[200:203], v[116:119]
	v_mfma_f32_16x16x32_bf16 v[124:127], v[132:135], v[200:203], v[124:127]
	v_mfma_f32_16x16x32_bf16 v[52:55], v[136:139], v[200:203], v[52:55]
	v_mfma_f32_16x16x32_bf16 v[60:63], v[140:143], v[200:203], v[60:63]
	ds_read_b128 v[200:203], v246 offset:5120
	s_waitcnt lgkmcnt(3)
	v_mfma_f32_16x16x32_bf16 v[96:99], v[128:131], v[204:207], v[96:99]
	v_mfma_f32_16x16x32_bf16 v[104:107], v[132:135], v[204:207], v[104:107]
	v_mfma_f32_16x16x32_bf16 v[32:35], v[136:139], v[204:207], v[32:35]
	v_mfma_f32_16x16x32_bf16 v[40:43], v[140:143], v[204:207], v[40:43]
	ds_read_b128 v[204:207], v246 offset:6144
	s_waitcnt lgkmcnt(3)
	v_mfma_f32_16x16x32_bf16 v[100:103], v[128:131], v[242:245], v[100:103]
	v_mfma_f32_16x16x32_bf16 v[108:111], v[132:135], v[242:245], v[108:111]
	v_mfma_f32_16x16x32_bf16 v[36:39], v[136:139], v[242:245], v[36:39]
	v_mfma_f32_16x16x32_bf16 v[44:47], v[140:143], v[242:245], v[44:47]
	ds_read_b128 v[242:245], v246 offset:7168
	s_waitcnt lgkmcnt(3)
	v_mfma_f32_16x16x32_bf16 v[80:83], v[128:131], v[196:199], v[80:83]
	v_mfma_f32_16x16x32_bf16 v[88:91], v[132:135], v[196:199], v[88:91]
	v_mfma_f32_16x16x32_bf16 v[16:19], v[136:139], v[196:199], v[16:19]
	v_mfma_f32_16x16x32_bf16 v[24:27], v[140:143], v[196:199], v[24:27]
	s_waitcnt lgkmcnt(2)
	v_mfma_f32_16x16x32_bf16 v[84:87], v[128:131], v[200:203], v[84:87]
	v_mfma_f32_16x16x32_bf16 v[92:95], v[132:135], v[200:203], v[92:95]
	v_mfma_f32_16x16x32_bf16 v[20:23], v[136:139], v[200:203], v[20:23]
	v_mfma_f32_16x16x32_bf16 v[28:31], v[140:143], v[200:203], v[28:31]
	s_waitcnt lgkmcnt(1)
	v_mfma_f32_16x16x32_bf16 v[64:67], v[128:131], v[204:207], v[64:67]
	v_mfma_f32_16x16x32_bf16 v[72:75], v[132:135], v[204:207], v[72:75]
	v_mfma_f32_16x16x32_bf16 v[0:3], v[136:139], v[204:207], v[0:3]
	v_mfma_f32_16x16x32_bf16 v[8:11], v[140:143], v[204:207], v[8:11]
	s_waitcnt lgkmcnt(0)
	v_mfma_f32_16x16x32_bf16 v[68:71], v[128:131], v[242:245], v[68:71]
	v_mfma_f32_16x16x32_bf16 v[76:79], v[132:135], v[242:245], v[76:79]
	v_mfma_f32_16x16x32_bf16 v[4:7], v[136:139], v[242:245], v[4:7]
	v_mfma_f32_16x16x32_bf16 v[12:15], v[140:143], v[242:245], v[12:15]
	s_waitcnt vmcnt(4)
	s_barrier
	ds_read_b128 v[196:199], v246 offset:8192
	ds_read_b128 v[200:203], v246 offset:9216
	ds_read_b128 v[204:207], v246 offset:10240
	ds_read_b128 v[242:245], v246 offset:11264
	s_waitcnt vmcnt(0) lgkmcnt(3)
	v_mfma_f32_16x16x32_bf16 v[112:115], v[144:147], v[196:199], v[112:115]
	v_mfma_f32_16x16x32_bf16 v[120:123], v[148:151], v[196:199], v[120:123]
	v_mfma_f32_16x16x32_bf16 v[48:51], v[152:155], v[196:199], v[48:51]
	v_mfma_f32_16x16x32_bf16 v[56:59], v[156:159], v[196:199], v[56:59]
	ds_read_b128 v[196:199], v246 offset:12288
	s_waitcnt lgkmcnt(3)
	v_mfma_f32_16x16x32_bf16 v[116:119], v[144:147], v[200:203], v[116:119]
	v_mfma_f32_16x16x32_bf16 v[124:127], v[148:151], v[200:203], v[124:127]
	v_mfma_f32_16x16x32_bf16 v[52:55], v[152:155], v[200:203], v[52:55]
	v_mfma_f32_16x16x32_bf16 v[60:63], v[156:159], v[200:203], v[60:63]
	ds_read_b128 v[200:203], v246 offset:13312
	s_waitcnt lgkmcnt(3)
	v_mfma_f32_16x16x32_bf16 v[96:99], v[144:147], v[204:207], v[96:99]
	v_mfma_f32_16x16x32_bf16 v[104:107], v[148:151], v[204:207], v[104:107]
	v_mfma_f32_16x16x32_bf16 v[32:35], v[152:155], v[204:207], v[32:35]
	v_mfma_f32_16x16x32_bf16 v[40:43], v[156:159], v[204:207], v[40:43]
	ds_read_b128 v[204:207], v246 offset:14336
	s_waitcnt lgkmcnt(3)
	v_mfma_f32_16x16x32_bf16 v[100:103], v[144:147], v[242:245], v[100:103]
	v_mfma_f32_16x16x32_bf16 v[108:111], v[148:151], v[242:245], v[108:111]
	v_mfma_f32_16x16x32_bf16 v[36:39], v[152:155], v[242:245], v[36:39]
	v_mfma_f32_16x16x32_bf16 v[44:47], v[156:159], v[242:245], v[44:47]
	ds_read_b128 v[242:245], v246 offset:15360
	v_permlane16_swap_b32_e32 v112, v116
	v_permlane16_swap_b32_e32 v113, v117
	v_permlane16_swap_b32_e32 v114, v118
	v_permlane16_swap_b32_e32 v115, v119
	v_permlane16_swap_b32_e32 v120, v124
	v_permlane16_swap_b32_e32 v121, v125
	v_permlane16_swap_b32_e32 v122, v126
	v_permlane16_swap_b32_e32 v123, v127
	v_permlane16_swap_b32_e32 v48, v52
	v_permlane16_swap_b32_e32 v49, v53
	v_permlane16_swap_b32_e32 v50, v54
	v_permlane16_swap_b32_e32 v51, v55
	v_permlane16_swap_b32_e32 v56, v60
	v_permlane16_swap_b32_e32 v57, v61
	v_permlane16_swap_b32_e32 v58, v62
	v_permlane16_swap_b32_e32 v59, v63
	v_permlane32_swap_b32_e32 v112, v116
	v_permlane32_swap_b32_e32 v113, v117
	v_permlane32_swap_b32_e32 v114, v118
	v_permlane32_swap_b32_e32 v115, v119
	v_permlane32_swap_b32_e32 v120, v124
	v_permlane32_swap_b32_e32 v121, v125
	v_permlane32_swap_b32_e32 v122, v126
	v_permlane32_swap_b32_e32 v123, v127
	v_permlane32_swap_b32_e32 v48, v52
	v_permlane32_swap_b32_e32 v49, v53
	v_permlane32_swap_b32_e32 v50, v54
	v_permlane32_swap_b32_e32 v51, v55
	v_permlane32_swap_b32_e32 v56, v60
	v_permlane32_swap_b32_e32 v57, v61
	v_permlane32_swap_b32_e32 v58, v62
	v_permlane32_swap_b32_e32 v59, v63
	s_waitcnt lgkmcnt(3)
	v_mfma_f32_16x16x32_bf16 v[80:83], v[144:147], v[196:199], v[80:83]
	v_mfma_f32_16x16x32_bf16 v[88:91], v[148:151], v[196:199], v[88:91]
	v_mfma_f32_16x16x32_bf16 v[16:19], v[152:155], v[196:199], v[16:19]
	v_mfma_f32_16x16x32_bf16 v[24:27], v[156:159], v[196:199], v[24:27]
	s_waitcnt lgkmcnt(2)
	v_mfma_f32_16x16x32_bf16 v[84:87], v[144:147], v[200:203], v[84:87]
	v_mfma_f32_16x16x32_bf16 v[92:95], v[148:151], v[200:203], v[92:95]
	v_mfma_f32_16x16x32_bf16 v[20:23], v[152:155], v[200:203], v[20:23]
	v_mfma_f32_16x16x32_bf16 v[28:31], v[156:159], v[200:203], v[28:31]
	v_permlane16_swap_b32_e32 v96, v100
	v_permlane16_swap_b32_e32 v97, v101
	v_permlane16_swap_b32_e32 v98, v102
	v_permlane16_swap_b32_e32 v99, v103
	v_permlane16_swap_b32_e32 v104, v108
	v_permlane16_swap_b32_e32 v105, v109
	v_permlane16_swap_b32_e32 v106, v110
	v_permlane16_swap_b32_e32 v107, v111
	v_permlane16_swap_b32_e32 v32, v36
	v_permlane16_swap_b32_e32 v33, v37
	v_permlane16_swap_b32_e32 v34, v38
	v_permlane16_swap_b32_e32 v35, v39
	v_permlane16_swap_b32_e32 v40, v44
	v_permlane16_swap_b32_e32 v41, v45
	v_permlane16_swap_b32_e32 v42, v46
	v_permlane16_swap_b32_e32 v43, v47
	v_permlane32_swap_b32_e32 v96, v100
	v_permlane32_swap_b32_e32 v97, v101
	v_permlane32_swap_b32_e32 v98, v102
	v_permlane32_swap_b32_e32 v99, v103
	v_permlane32_swap_b32_e32 v104, v108
	v_permlane32_swap_b32_e32 v105, v109
	v_permlane32_swap_b32_e32 v106, v110
	v_permlane32_swap_b32_e32 v107, v111
	v_permlane32_swap_b32_e32 v32, v36
	v_permlane32_swap_b32_e32 v33, v37
	v_permlane32_swap_b32_e32 v34, v38
	v_permlane32_swap_b32_e32 v35, v39
	v_permlane32_swap_b32_e32 v40, v44
	v_permlane32_swap_b32_e32 v41, v45
	v_permlane32_swap_b32_e32 v42, v46
	v_permlane32_swap_b32_e32 v43, v47
	s_waitcnt lgkmcnt(1)
	v_mfma_f32_16x16x32_bf16 v[64:67], v[144:147], v[204:207], v[64:67]
	v_mfma_f32_16x16x32_bf16 v[72:75], v[148:151], v[204:207], v[72:75]
	v_mfma_f32_16x16x32_bf16 v[0:3], v[152:155], v[204:207], v[0:3]
	v_mfma_f32_16x16x32_bf16 v[8:11], v[156:159], v[204:207], v[8:11]
	s_waitcnt lgkmcnt(0)
	v_mfma_f32_16x16x32_bf16 v[68:71], v[144:147], v[242:245], v[68:71]
	v_mfma_f32_16x16x32_bf16 v[76:79], v[148:151], v[242:245], v[76:79]
	v_mfma_f32_16x16x32_bf16 v[4:7], v[152:155], v[242:245], v[4:7]
	v_mfma_f32_16x16x32_bf16 v[12:15], v[156:159], v[242:245], v[12:15]
	v_permlane16_swap_b32_e32 v80, v84
	v_permlane16_swap_b32_e32 v81, v85
	v_permlane16_swap_b32_e32 v82, v86
	v_permlane16_swap_b32_e32 v83, v87
	v_permlane16_swap_b32_e32 v88, v92
	v_permlane16_swap_b32_e32 v89, v93
	v_permlane16_swap_b32_e32 v90, v94
	v_permlane16_swap_b32_e32 v91, v95
	v_permlane16_swap_b32_e32 v16, v20
	v_permlane16_swap_b32_e32 v17, v21
	v_permlane16_swap_b32_e32 v18, v22
	v_permlane16_swap_b32_e32 v19, v23
	v_permlane16_swap_b32_e32 v24, v28
	v_permlane16_swap_b32_e32 v25, v29
	v_permlane16_swap_b32_e32 v26, v30
	v_permlane16_swap_b32_e32 v27, v31
	v_permlane32_swap_b32_e32 v80, v84
	v_permlane32_swap_b32_e32 v81, v85
	v_permlane32_swap_b32_e32 v82, v86
	v_permlane32_swap_b32_e32 v83, v87
	v_permlane32_swap_b32_e32 v88, v92
	v_permlane32_swap_b32_e32 v89, v93
	v_permlane32_swap_b32_e32 v90, v94
	v_permlane32_swap_b32_e32 v91, v95
	v_permlane32_swap_b32_e32 v16, v20
	v_permlane32_swap_b32_e32 v17, v21
	v_permlane32_swap_b32_e32 v18, v22
	v_permlane32_swap_b32_e32 v19, v23
	v_permlane32_swap_b32_e32 v24, v28
	v_permlane32_swap_b32_e32 v25, v29
	v_permlane32_swap_b32_e32 v26, v30
	v_permlane32_swap_b32_e32 v27, v31
	s_barrier
	s_nop 7
	v_permlane16_swap_b32_e32 v64, v68
	v_permlane16_swap_b32_e32 v65, v69
	v_permlane16_swap_b32_e32 v66, v70
	v_permlane16_swap_b32_e32 v67, v71
	v_permlane16_swap_b32_e32 v72, v76
	v_permlane16_swap_b32_e32 v73, v77
	v_permlane16_swap_b32_e32 v74, v78
	v_permlane16_swap_b32_e32 v75, v79
	v_permlane16_swap_b32_e32 v0, v4
	v_permlane16_swap_b32_e32 v1, v5
	v_permlane16_swap_b32_e32 v2, v6
	v_permlane16_swap_b32_e32 v3, v7
	v_permlane16_swap_b32_e32 v8, v12
	v_permlane16_swap_b32_e32 v9, v13
	v_permlane16_swap_b32_e32 v10, v14
	v_permlane16_swap_b32_e32 v11, v15
	v_permlane32_swap_b32_e32 v64, v68
	v_permlane32_swap_b32_e32 v65, v69
	v_permlane32_swap_b32_e32 v66, v70
	v_permlane32_swap_b32_e32 v67, v71
	v_permlane32_swap_b32_e32 v72, v76
	v_permlane32_swap_b32_e32 v73, v77
	v_permlane32_swap_b32_e32 v74, v78
	v_permlane32_swap_b32_e32 v75, v79
	v_permlane32_swap_b32_e32 v0, v4
	v_permlane32_swap_b32_e32 v1, v5
	v_permlane32_swap_b32_e32 v2, v6
	v_permlane32_swap_b32_e32 v3, v7
	v_permlane32_swap_b32_e32 v8, v12
	v_permlane32_swap_b32_e32 v9, v13
	v_permlane32_swap_b32_e32 v10, v14
	v_permlane32_swap_b32_e32 v11, v15
	s_waitcnt vmcnt(0)
	s_waitcnt vmcnt(0)
	v_and_b32_e32 v188, 63, v179
	v_lshrrev_b32_e32 v189, 6, v179
	v_mul_u32_u24_e32 v249, 0x2400, v189
	v_mov_b32_e32 v250, v249
	v_lshrrev_b32_e32 v251, 5, v188
	v_mul_u32_u24_e32 v251, 0x440, v251
	v_add_u32_e32 v249, v249, v251
	v_and_b32_e32 v251, 31, v188
	v_lshl_add_u32 v249, v251, 2, v249
	v_lshrrev_b32_e32 v237, 4, v188
	v_mul_u32_u24_e32 v251, 0x110, v237
	v_add_u32_e32 v250, v250, v251
	v_and_b32_e32 v251, 15, v188
	v_lshlrev_b32_e32 v251, 4, v251
	v_add_u32_e32 v250, v250, v251
	v_lshl_add_u32 v237, v189, 6, v237
	v_lshl_add_u32 v237, v237, 12, v251
	v_add_u32_e32 v238, 16384, v237
	v_add_u32_e32 v239, 32768, v237
	v_add_u32_e32 v240, 49152, v237
	v_add_u32_e32 v241, 65536, v237
	v_add_u32_e32 v242, 81920, v237
	v_add_u32_e32 v243, 98304, v237
	v_add_u32_e32 v248, 114688, v237
	s_lshl_b32 s16, s8, 8
	s_lshl_b32 s18, s2, 9
	s_lshr_b32 s19, s8, 4
	v_readlane_b32 s12, v254, 38
	v_readlane_b32 s13, v254, 37
	v_readlane_b32 s14, v253, 46
	v_readlane_b32 s15, v253, 47
	v_readlane_b32 s22, v254, 40
	v_readlane_b32 s23, v254, 39
	s_add_i32 s17, s16, 0xffff8000
	s_cmpk_lt_u32 s8, 0x80
	s_cselect_b32 s12, s12, s22
	s_cselect_b32 s13, s13, s23
	s_cselect_b32 s14, s14, s62
	s_cselect_b32 s15, s15, s63
	s_cselect_b32 s19, s19, 8
	s_cselect_b32 s16, s16, s17
	s_mov_b32 s17, 0
	s_lshl_b64 s[16:17], s[16:17], 12
	s_add_u32 s16, s16, s18
	s_addc_u32 s17, s17, 0
	s_add_u32 s12, s12, s16
	s_addc_u32 s13, s13, s17
	s_add_u32 s14, s14, s16
	s_addc_u32 s15, s15, s17
	s_mul_i32 s19, s19, 0x6000
	s_add_u32 s20, s0, s19
	s_addc_u32 s21, s1, 0
	s_add_u32 s20, s20, s18
	s_addc_u32 s21, s21, 0
	global_load_dwordx4 v[244:247], v251, s[20:21]
	global_load_dwordx4 v[160:163], v237, s[12:13]
	global_load_dwordx4 v[164:167], v238, s[12:13]
	global_load_dwordx4 v[168:171], v239, s[12:13]
	global_load_dwordx4 v[172:175], v240, s[12:13]
	global_load_dwordx4 v[196:199], v241, s[12:13]
	global_load_dwordx4 v[200:203], v242, s[12:13]
	global_load_dwordx4 v[204:207], v243, s[12:13]
	global_load_dwordx4 v[184:187], v248, s[12:13]
	ds_write_b32 v249, v112
	ds_write_b32 v249, v113 offset:272
	ds_write_b32 v249, v114 offset:544
	ds_write_b32 v249, v115 offset:816
	ds_write_b32 v249, v116 offset:2176
	ds_write_b32 v249, v117 offset:2448
	ds_write_b32 v249, v118 offset:2720
	ds_write_b32 v249, v119 offset:2992
	ds_write_b32 v249, v120 offset:4352
	ds_write_b32 v249, v121 offset:4624
	ds_write_b32 v249, v122 offset:4896
	ds_write_b32 v249, v123 offset:5168
	ds_write_b32 v249, v124 offset:6528
	ds_write_b32 v249, v125 offset:6800
	ds_write_b32 v249, v126 offset:7072
	ds_write_b32 v249, v127 offset:7344
	ds_write_b32 v249, v96 offset:128
	ds_write_b32 v249, v97 offset:400
	ds_write_b32 v249, v98 offset:672
	ds_write_b32 v249, v99 offset:944
	ds_write_b32 v249, v100 offset:2304
	ds_write_b32 v249, v101 offset:2576
	ds_write_b32 v249, v102 offset:2848
	ds_write_b32 v249, v103 offset:3120
	ds_write_b32 v249, v104 offset:4480
	ds_write_b32 v249, v105 offset:4752
	ds_write_b32 v249, v106 offset:5024
	ds_write_b32 v249, v107 offset:5296
	ds_write_b32 v249, v108 offset:6656
	ds_write_b32 v249, v109 offset:6928
	ds_write_b32 v249, v110 offset:7200
	ds_write_b32 v249, v111 offset:7472
	s_waitcnt lgkmcnt(0)
	ds_read_b128 v[128:131], v250
	ds_read_b128 v[132:135], v250 offset:1088
	ds_read_b128 v[136:139], v250 offset:2176
	ds_read_b128 v[140:143], v250 offset:3264
	ds_read_b128 v[144:147], v250 offset:4352
	ds_read_b128 v[148:151], v250 offset:5440
	ds_read_b128 v[152:155], v250 offset:6528
	ds_read_b128 v[156:159], v250 offset:7616
	s_waitcnt vmcnt(7) lgkmcnt(7)
	v_fma_f32 v128, v244, v128, v160
	v_fma_f32 v129, v245, v129, v161
	v_fma_f32 v130, v246, v130, v162
	v_fma_f32 v131, v247, v131, v163
	global_store_dwordx4 v237, v[128:131], s[14:15]
	s_waitcnt vmcnt(7) lgkmcnt(6)
	v_fma_f32 v132, v244, v132, v164
	v_fma_f32 v133, v245, v133, v165
	v_fma_f32 v134, v246, v134, v166
	v_fma_f32 v135, v247, v135, v167
	global_store_dwordx4 v238, v[132:135], s[14:15]
	s_waitcnt vmcnt(7) lgkmcnt(5)
	v_fma_f32 v136, v244, v136, v168
	v_fma_f32 v137, v245, v137, v169
	v_fma_f32 v138, v246, v138, v170
	v_fma_f32 v139, v247, v139, v171
	global_store_dwordx4 v239, v[136:139], s[14:15]
	s_waitcnt vmcnt(7) lgkmcnt(4)
	v_fma_f32 v140, v244, v140, v172
	v_fma_f32 v141, v245, v141, v173
	v_fma_f32 v142, v246, v142, v174
	v_fma_f32 v143, v247, v143, v175
	global_store_dwordx4 v240, v[140:143], s[14:15]
	s_waitcnt vmcnt(7) lgkmcnt(3)
	v_fma_f32 v144, v244, v144, v196
	v_fma_f32 v145, v245, v145, v197
	v_fma_f32 v146, v246, v146, v198
	v_fma_f32 v147, v247, v147, v199
	global_store_dwordx4 v241, v[144:147], s[14:15]
	s_waitcnt vmcnt(7) lgkmcnt(2)
	v_fma_f32 v148, v244, v148, v200
	v_fma_f32 v149, v245, v149, v201
	v_fma_f32 v150, v246, v150, v202
	v_fma_f32 v151, v247, v151, v203
	global_store_dwordx4 v242, v[148:151], s[14:15]
	s_waitcnt vmcnt(7) lgkmcnt(1)
	v_fma_f32 v152, v244, v152, v204
	v_fma_f32 v153, v245, v153, v205
	v_fma_f32 v154, v246, v154, v206
	v_fma_f32 v155, v247, v155, v207
	global_store_dwordx4 v243, v[152:155], s[14:15]
	s_waitcnt vmcnt(7) lgkmcnt(0)
	v_fma_f32 v156, v244, v156, v184
	v_fma_f32 v157, v245, v157, v185
	v_fma_f32 v158, v246, v158, v186
	v_fma_f32 v159, v247, v159, v187
	global_store_dwordx4 v248, v[156:159], s[14:15]
	global_load_dwordx4 v[244:247], v251, s[20:21] offset:256
	global_load_dwordx4 v[160:163], v237, s[12:13] offset:256
	global_load_dwordx4 v[164:167], v238, s[12:13] offset:256
	global_load_dwordx4 v[168:171], v239, s[12:13] offset:256
	global_load_dwordx4 v[172:175], v240, s[12:13] offset:256
	global_load_dwordx4 v[196:199], v241, s[12:13] offset:256
	global_load_dwordx4 v[200:203], v242, s[12:13] offset:256
	global_load_dwordx4 v[204:207], v243, s[12:13] offset:256
	global_load_dwordx4 v[184:187], v248, s[12:13] offset:256
	ds_write_b32 v249, v80
	ds_write_b32 v249, v81 offset:272
	ds_write_b32 v249, v82 offset:544
	ds_write_b32 v249, v83 offset:816
	ds_write_b32 v249, v84 offset:2176
	ds_write_b32 v249, v85 offset:2448
	ds_write_b32 v249, v86 offset:2720
	ds_write_b32 v249, v87 offset:2992
	ds_write_b32 v249, v88 offset:4352
	ds_write_b32 v249, v89 offset:4624
	ds_write_b32 v249, v90 offset:4896
	ds_write_b32 v249, v91 offset:5168
	ds_write_b32 v249, v92 offset:6528
	ds_write_b32 v249, v93 offset:6800
	ds_write_b32 v249, v94 offset:7072
	ds_write_b32 v249, v95 offset:7344
	ds_write_b32 v249, v64 offset:128
	ds_write_b32 v249, v65 offset:400
	ds_write_b32 v249, v66 offset:672
	ds_write_b32 v249, v67 offset:944
	ds_write_b32 v249, v68 offset:2304
	ds_write_b32 v249, v69 offset:2576
	ds_write_b32 v249, v70 offset:2848
	ds_write_b32 v249, v71 offset:3120
	ds_write_b32 v249, v72 offset:4480
	ds_write_b32 v249, v73 offset:4752
	ds_write_b32 v249, v74 offset:5024
	ds_write_b32 v249, v75 offset:5296
	ds_write_b32 v249, v76 offset:6656
	ds_write_b32 v249, v77 offset:6928
	ds_write_b32 v249, v78 offset:7200
	ds_write_b32 v249, v79 offset:7472
	s_waitcnt lgkmcnt(0)
	ds_read_b128 v[128:131], v250
	ds_read_b128 v[132:135], v250 offset:1088
	ds_read_b128 v[136:139], v250 offset:2176
	ds_read_b128 v[140:143], v250 offset:3264
	ds_read_b128 v[144:147], v250 offset:4352
	ds_read_b128 v[148:151], v250 offset:5440
	ds_read_b128 v[152:155], v250 offset:6528
	ds_read_b128 v[156:159], v250 offset:7616
	s_waitcnt vmcnt(7) lgkmcnt(7)
	v_fma_f32 v128, v244, v128, v160
	v_fma_f32 v129, v245, v129, v161
	v_fma_f32 v130, v246, v130, v162
	v_fma_f32 v131, v247, v131, v163
	global_store_dwordx4 v237, v[128:131], s[14:15] offset:256
	s_waitcnt vmcnt(7) lgkmcnt(6)
	v_fma_f32 v132, v244, v132, v164
	v_fma_f32 v133, v245, v133, v165
	v_fma_f32 v134, v246, v134, v166
	v_fma_f32 v135, v247, v135, v167
	global_store_dwordx4 v238, v[132:135], s[14:15] offset:256
	s_waitcnt vmcnt(7) lgkmcnt(5)
	v_fma_f32 v136, v244, v136, v168
	v_fma_f32 v137, v245, v137, v169
	v_fma_f32 v138, v246, v138, v170
	v_fma_f32 v139, v247, v139, v171
	global_store_dwordx4 v239, v[136:139], s[14:15] offset:256
	s_waitcnt vmcnt(7) lgkmcnt(4)
	v_fma_f32 v140, v244, v140, v172
	v_fma_f32 v141, v245, v141, v173
	v_fma_f32 v142, v246, v142, v174
	v_fma_f32 v143, v247, v143, v175
	global_store_dwordx4 v240, v[140:143], s[14:15] offset:256
	s_waitcnt vmcnt(7) lgkmcnt(3)
	v_fma_f32 v144, v244, v144, v196
	v_fma_f32 v145, v245, v145, v197
	v_fma_f32 v146, v246, v146, v198
	v_fma_f32 v147, v247, v147, v199
	global_store_dwordx4 v241, v[144:147], s[14:15] offset:256
	s_waitcnt vmcnt(7) lgkmcnt(2)
	v_fma_f32 v148, v244, v148, v200
	v_fma_f32 v149, v245, v149, v201
	v_fma_f32 v150, v246, v150, v202
	v_fma_f32 v151, v247, v151, v203
	global_store_dwordx4 v242, v[148:151], s[14:15] offset:256
	s_waitcnt vmcnt(7) lgkmcnt(1)
	v_fma_f32 v152, v244, v152, v204
	v_fma_f32 v153, v245, v153, v205
	v_fma_f32 v154, v246, v154, v206
	v_fma_f32 v155, v247, v155, v207
	global_store_dwordx4 v243, v[152:155], s[14:15] offset:256
	s_waitcnt vmcnt(7) lgkmcnt(0)
	v_fma_f32 v156, v244, v156, v184
	v_fma_f32 v157, v245, v157, v185
	v_fma_f32 v158, v246, v158, v186
	v_fma_f32 v159, v247, v159, v187
	global_store_dwordx4 v248, v[156:159], s[14:15] offset:256
	s_add_u32 s12, s12, 0x20000
	s_addc_u32 s13, s13, 0
	s_add_u32 s14, s14, 0x20000
	s_addc_u32 s15, s15, 0
	global_load_dwordx4 v[244:247], v251, s[20:21]
	global_load_dwordx4 v[160:163], v237, s[12:13]
	global_load_dwordx4 v[164:167], v238, s[12:13]
	global_load_dwordx4 v[168:171], v239, s[12:13]
	global_load_dwordx4 v[172:175], v240, s[12:13]
	global_load_dwordx4 v[196:199], v241, s[12:13]
	global_load_dwordx4 v[200:203], v242, s[12:13]
	global_load_dwordx4 v[204:207], v243, s[12:13]
	global_load_dwordx4 v[184:187], v248, s[12:13]
	ds_write_b32 v249, v48
	ds_write_b32 v249, v49 offset:272
	ds_write_b32 v249, v50 offset:544
	ds_write_b32 v249, v51 offset:816
	ds_write_b32 v249, v52 offset:2176
	ds_write_b32 v249, v53 offset:2448
	ds_write_b32 v249, v54 offset:2720
	ds_write_b32 v249, v55 offset:2992
	ds_write_b32 v249, v56 offset:4352
	ds_write_b32 v249, v57 offset:4624
	ds_write_b32 v249, v58 offset:4896
	ds_write_b32 v249, v59 offset:5168
	ds_write_b32 v249, v60 offset:6528
	ds_write_b32 v249, v61 offset:6800
	ds_write_b32 v249, v62 offset:7072
	ds_write_b32 v249, v63 offset:7344
	ds_write_b32 v249, v32 offset:128
	ds_write_b32 v249, v33 offset:400
	ds_write_b32 v249, v34 offset:672
	ds_write_b32 v249, v35 offset:944
	ds_write_b32 v249, v36 offset:2304
	ds_write_b32 v249, v37 offset:2576
	ds_write_b32 v249, v38 offset:2848
	ds_write_b32 v249, v39 offset:3120
	ds_write_b32 v249, v40 offset:4480
	ds_write_b32 v249, v41 offset:4752
	ds_write_b32 v249, v42 offset:5024
	ds_write_b32 v249, v43 offset:5296
	ds_write_b32 v249, v44 offset:6656
	ds_write_b32 v249, v45 offset:6928
	ds_write_b32 v249, v46 offset:7200
	ds_write_b32 v249, v47 offset:7472
	s_waitcnt lgkmcnt(0)
	ds_read_b128 v[128:131], v250
	ds_read_b128 v[132:135], v250 offset:1088
	ds_read_b128 v[136:139], v250 offset:2176
	ds_read_b128 v[140:143], v250 offset:3264
	ds_read_b128 v[144:147], v250 offset:4352
	ds_read_b128 v[148:151], v250 offset:5440
	ds_read_b128 v[152:155], v250 offset:6528
	ds_read_b128 v[156:159], v250 offset:7616
	s_waitcnt vmcnt(7) lgkmcnt(7)
	v_fma_f32 v128, v244, v128, v160
	v_fma_f32 v129, v245, v129, v161
	v_fma_f32 v130, v246, v130, v162
	v_fma_f32 v131, v247, v131, v163
	global_store_dwordx4 v237, v[128:131], s[14:15]
	s_waitcnt vmcnt(7) lgkmcnt(6)
	v_fma_f32 v132, v244, v132, v164
	v_fma_f32 v133, v245, v133, v165
	v_fma_f32 v134, v246, v134, v166
	v_fma_f32 v135, v247, v135, v167
	global_store_dwordx4 v238, v[132:135], s[14:15]
	s_waitcnt vmcnt(7) lgkmcnt(5)
	v_fma_f32 v136, v244, v136, v168
	v_fma_f32 v137, v245, v137, v169
	v_fma_f32 v138, v246, v138, v170
	v_fma_f32 v139, v247, v139, v171
	global_store_dwordx4 v239, v[136:139], s[14:15]
	s_waitcnt vmcnt(7) lgkmcnt(4)
	v_fma_f32 v140, v244, v140, v172
	v_fma_f32 v141, v245, v141, v173
	v_fma_f32 v142, v246, v142, v174
	v_fma_f32 v143, v247, v143, v175
	global_store_dwordx4 v240, v[140:143], s[14:15]
	s_waitcnt vmcnt(7) lgkmcnt(3)
	v_fma_f32 v144, v244, v144, v196
	v_fma_f32 v145, v245, v145, v197
	v_fma_f32 v146, v246, v146, v198
	v_fma_f32 v147, v247, v147, v199
	global_store_dwordx4 v241, v[144:147], s[14:15]
	s_waitcnt vmcnt(7) lgkmcnt(2)
	v_fma_f32 v148, v244, v148, v200
	v_fma_f32 v149, v245, v149, v201
	v_fma_f32 v150, v246, v150, v202
	v_fma_f32 v151, v247, v151, v203
	global_store_dwordx4 v242, v[148:151], s[14:15]
	s_waitcnt vmcnt(7) lgkmcnt(1)
	v_fma_f32 v152, v244, v152, v204
	v_fma_f32 v153, v245, v153, v205
	v_fma_f32 v154, v246, v154, v206
	v_fma_f32 v155, v247, v155, v207
	global_store_dwordx4 v243, v[152:155], s[14:15]
	s_waitcnt vmcnt(7) lgkmcnt(0)
	v_fma_f32 v156, v244, v156, v184
	v_fma_f32 v157, v245, v157, v185
	v_fma_f32 v158, v246, v158, v186
	v_fma_f32 v159, v247, v159, v187
	global_store_dwordx4 v248, v[156:159], s[14:15]
	global_load_dwordx4 v[244:247], v251, s[20:21] offset:256
	global_load_dwordx4 v[160:163], v237, s[12:13] offset:256
	global_load_dwordx4 v[164:167], v238, s[12:13] offset:256
	global_load_dwordx4 v[168:171], v239, s[12:13] offset:256
	global_load_dwordx4 v[172:175], v240, s[12:13] offset:256
	global_load_dwordx4 v[196:199], v241, s[12:13] offset:256
	global_load_dwordx4 v[200:203], v242, s[12:13] offset:256
	global_load_dwordx4 v[204:207], v243, s[12:13] offset:256
	global_load_dwordx4 v[184:187], v248, s[12:13] offset:256
	ds_write_b32 v249, v16
	ds_write_b32 v249, v17 offset:272
	ds_write_b32 v249, v18 offset:544
	ds_write_b32 v249, v19 offset:816
	ds_write_b32 v249, v20 offset:2176
	ds_write_b32 v249, v21 offset:2448
	ds_write_b32 v249, v22 offset:2720
	ds_write_b32 v249, v23 offset:2992
	ds_write_b32 v249, v24 offset:4352
	ds_write_b32 v249, v25 offset:4624
	ds_write_b32 v249, v26 offset:4896
	ds_write_b32 v249, v27 offset:5168
	ds_write_b32 v249, v28 offset:6528
	ds_write_b32 v249, v29 offset:6800
	ds_write_b32 v249, v30 offset:7072
	ds_write_b32 v249, v31 offset:7344
	ds_write_b32 v249, v0 offset:128
	ds_write_b32 v249, v1 offset:400
	ds_write_b32 v249, v2 offset:672
	ds_write_b32 v249, v3 offset:944
	ds_write_b32 v249, v4 offset:2304
	ds_write_b32 v249, v5 offset:2576
	ds_write_b32 v249, v6 offset:2848
	ds_write_b32 v249, v7 offset:3120
	ds_write_b32 v249, v8 offset:4480
	ds_write_b32 v249, v9 offset:4752
	ds_write_b32 v249, v10 offset:5024
	ds_write_b32 v249, v11 offset:5296
	ds_write_b32 v249, v12 offset:6656
	ds_write_b32 v249, v13 offset:6928
	ds_write_b32 v249, v14 offset:7200
	ds_write_b32 v249, v15 offset:7472
	s_waitcnt lgkmcnt(0)
	ds_read_b128 v[128:131], v250
	ds_read_b128 v[132:135], v250 offset:1088
	ds_read_b128 v[136:139], v250 offset:2176
	ds_read_b128 v[140:143], v250 offset:3264
	ds_read_b128 v[144:147], v250 offset:4352
	ds_read_b128 v[148:151], v250 offset:5440
	ds_read_b128 v[152:155], v250 offset:6528
	ds_read_b128 v[156:159], v250 offset:7616
	s_waitcnt vmcnt(7) lgkmcnt(7)
	v_fma_f32 v128, v244, v128, v160
	v_fma_f32 v129, v245, v129, v161
	v_fma_f32 v130, v246, v130, v162
	v_fma_f32 v131, v247, v131, v163
	global_store_dwordx4 v237, v[128:131], s[14:15] offset:256
	s_waitcnt vmcnt(7) lgkmcnt(6)
	v_fma_f32 v132, v244, v132, v164
	v_fma_f32 v133, v245, v133, v165
	v_fma_f32 v134, v246, v134, v166
	v_fma_f32 v135, v247, v135, v167
	global_store_dwordx4 v238, v[132:135], s[14:15] offset:256
	s_waitcnt vmcnt(7) lgkmcnt(5)
	v_fma_f32 v136, v244, v136, v168
	v_fma_f32 v137, v245, v137, v169
	v_fma_f32 v138, v246, v138, v170
	v_fma_f32 v139, v247, v139, v171
	global_store_dwordx4 v239, v[136:139], s[14:15] offset:256
	s_waitcnt vmcnt(7) lgkmcnt(4)
	v_fma_f32 v140, v244, v140, v172
	v_fma_f32 v141, v245, v141, v173
	v_fma_f32 v142, v246, v142, v174
	v_fma_f32 v143, v247, v143, v175
	global_store_dwordx4 v240, v[140:143], s[14:15] offset:256
	s_waitcnt vmcnt(7) lgkmcnt(3)
	v_fma_f32 v144, v244, v144, v196
	v_fma_f32 v145, v245, v145, v197
	v_fma_f32 v146, v246, v146, v198
	v_fma_f32 v147, v247, v147, v199
	global_store_dwordx4 v241, v[144:147], s[14:15] offset:256
	s_waitcnt vmcnt(7) lgkmcnt(2)
	v_fma_f32 v148, v244, v148, v200
	v_fma_f32 v149, v245, v149, v201
	v_fma_f32 v150, v246, v150, v202
	v_fma_f32 v151, v247, v151, v203
	global_store_dwordx4 v242, v[148:151], s[14:15] offset:256
	s_waitcnt vmcnt(7) lgkmcnt(1)
	v_fma_f32 v152, v244, v152, v204
	v_fma_f32 v153, v245, v153, v205
	v_fma_f32 v154, v246, v154, v206
	v_fma_f32 v155, v247, v155, v207
	global_store_dwordx4 v243, v[152:155], s[14:15] offset:256
	s_waitcnt vmcnt(7) lgkmcnt(0)
	v_fma_f32 v156, v244, v156, v184
	v_fma_f32 v157, v245, v157, v185
	v_fma_f32 v158, v246, v158, v186
	v_fma_f32 v159, v247, v159, v187
	global_store_dwordx4 v248, v[156:159], s[14:15] offset:256
	s_waitcnt lgkmcnt(0)
	v_readlane_b32 s2, v254, 11
	s_add_i32 s4, s4, s2
	s_cmp_lt_i32 s4, s26
	s_barrier
	s_cbranch_scc1 .LBB0_923

.Lg16_down_k:
	s_add_i32 s9, s8, 2
	s_lshl_b32 s96, s9, 13
	s_add_i32 m0, vcc_lo, 16384
	v_lshl_add_u64 v[160:161], v[188:189], 0, s[96:97]
	global_load_lds_dwordx4 v[160:161], off
	global_load_lds_dwordx4 v[160:161], off offset:1024
	ds_read_b128 v[196:199], v246 offset:0
	ds_read_b128 v[200:203], v246 offset:1024
	ds_read_b128 v[204:207], v246 offset:2048
	ds_read_b128 v[242:245], v246 offset:3072
	s_add_i32 s9, s8, 2
	s_lshl_b32 s96, s9, 11
	v_lshl_add_u64 v[248:249], v[184:185], 0, s[96:97]
	v_lshl_add_u64 v[250:251], v[186:187], 0, s[96:97]
	s_waitcnt vmcnt(8) lgkmcnt(3)
	v_mfma_f32_16x16x32_bf16 v[112:115], v[128:131], v[196:199], v[112:115]
	v_mfma_f32_16x16x32_bf16 v[120:123], v[132:135], v[196:199], v[120:123]
	v_mfma_f32_16x16x32_bf16 v[48:51], v[136:139], v[196:199], v[48:51]
	v_mfma_f32_16x16x32_bf16 v[56:59], v[140:143], v[196:199], v[56:59]
	ds_read_b128 v[196:199], v246 offset:4096
	s_waitcnt lgkmcnt(3)
	v_mfma_f32_16x16x32_bf16 v[116:119], v[128:131], v[200:203], v[116:119]
	v_mfma_f32_16x16x32_bf16 v[124:127], v[132:135], v[200:203], v[124:127]
	v_mfma_f32_16x16x32_bf16 v[52:55], v[136:139], v[200:203], v[52:55]
	v_mfma_f32_16x16x32_bf16 v[60:63], v[140:143], v[200:203], v[60:63]
	ds_read_b128 v[200:203], v246 offset:5120
	s_waitcnt lgkmcnt(3)
	v_mfma_f32_16x16x32_bf16 v[96:99], v[128:131], v[204:207], v[96:99]
	v_mfma_f32_16x16x32_bf16 v[104:107], v[132:135], v[204:207], v[104:107]
	v_mfma_f32_16x16x32_bf16 v[32:35], v[136:139], v[204:207], v[32:35]
	v_mfma_f32_16x16x32_bf16 v[40:43], v[140:143], v[204:207], v[40:43]
	ds_read_b128 v[204:207], v246 offset:6144
	s_waitcnt lgkmcnt(3)
	v_mfma_f32_16x16x32_bf16 v[100:103], v[128:131], v[242:245], v[100:103]
	v_mfma_f32_16x16x32_bf16 v[108:111], v[132:135], v[242:245], v[108:111]
	v_mfma_f32_16x16x32_bf16 v[36:39], v[136:139], v[242:245], v[36:39]
	v_mfma_f32_16x16x32_bf16 v[44:47], v[140:143], v[242:245], v[44:47]
	ds_read_b128 v[242:245], v246 offset:7168
	s_waitcnt lgkmcnt(3)
	v_mfma_f32_16x16x32_bf16 v[80:83], v[128:131], v[196:199], v[80:83]
	v_mfma_f32_16x16x32_bf16 v[88:91], v[132:135], v[196:199], v[88:91]
	v_mfma_f32_16x16x32_bf16 v[16:19], v[136:139], v[196:199], v[16:19]
	v_mfma_f32_16x16x32_bf16 v[24:27], v[140:143], v[196:199], v[24:27]
	s_waitcnt lgkmcnt(2)
	v_mfma_f32_16x16x32_bf16 v[84:87], v[128:131], v[200:203], v[84:87]
	v_mfma_f32_16x16x32_bf16 v[92:95], v[132:135], v[200:203], v[92:95]
	v_mfma_f32_16x16x32_bf16 v[20:23], v[136:139], v[200:203], v[20:23]
	v_mfma_f32_16x16x32_bf16 v[28:31], v[140:143], v[200:203], v[28:31]
	s_waitcnt lgkmcnt(1)
	v_mfma_f32_16x16x32_bf16 v[64:67], v[128:131], v[204:207], v[64:67]
	v_mfma_f32_16x16x32_bf16 v[72:75], v[132:135], v[204:207], v[72:75]
	v_mfma_f32_16x16x32_bf16 v[0:3], v[136:139], v[204:207], v[0:3]
	v_mfma_f32_16x16x32_bf16 v[8:11], v[140:143], v[204:207], v[8:11]
	s_waitcnt lgkmcnt(0)
	v_mfma_f32_16x16x32_bf16 v[68:71], v[128:131], v[242:245], v[68:71]
	v_mfma_f32_16x16x32_bf16 v[76:79], v[132:135], v[242:245], v[76:79]
	v_mfma_f32_16x16x32_bf16 v[4:7], v[136:139], v[242:245], v[4:7]
	v_mfma_f32_16x16x32_bf16 v[12:15], v[140:143], v[242:245], v[12:15]
	global_load_dwordx4 v[128:131], v[248:249], off
	global_load_dwordx4 v[132:135], v[248:249], off offset:256
	global_load_dwordx4 v[136:139], v[250:251], off
	global_load_dwordx4 v[140:143], v[250:251], off offset:256
	s_waitcnt vmcnt(10)
	s_barrier
	s_add_i32 s9, s8, 3
	s_lshl_b32 s96, s9, 13
	s_mov_b32 m0, vcc_lo
	v_lshl_add_u64 v[160:161], v[188:189], 0, s[96:97]
	global_load_lds_dwordx4 v[160:161], off
	global_load_lds_dwordx4 v[160:161], off offset:1024
	ds_read_b128 v[196:199], v246 offset:8192
	ds_read_b128 v[200:203], v246 offset:9216
	ds_read_b128 v[204:207], v246 offset:10240
	ds_read_b128 v[242:245], v246 offset:11264
	s_add_i32 s9, s8, 3
	s_lshl_b32 s96, s9, 11
	v_lshl_add_u64 v[248:249], v[184:185], 0, s[96:97]
	v_lshl_add_u64 v[250:251], v[186:187], 0, s[96:97]
	s_waitcnt vmcnt(8) lgkmcnt(3)
	v_mfma_f32_16x16x32_bf16 v[112:115], v[144:147], v[196:199], v[112:115]
	v_mfma_f32_16x16x32_bf16 v[120:123], v[148:151], v[196:199], v[120:123]
	v_mfma_f32_16x16x32_bf16 v[48:51], v[152:155], v[196:199], v[48:51]
	v_mfma_f32_16x16x32_bf16 v[56:59], v[156:159], v[196:199], v[56:59]
	ds_read_b128 v[196:199], v246 offset:12288
	s_waitcnt lgkmcnt(3)
	v_mfma_f32_16x16x32_bf16 v[116:119], v[144:147], v[200:203], v[116:119]
	v_mfma_f32_16x16x32_bf16 v[124:127], v[148:151], v[200:203], v[124:127]
	v_mfma_f32_16x16x32_bf16 v[52:55], v[152:155], v[200:203], v[52:55]
	v_mfma_f32_16x16x32_bf16 v[60:63], v[156:159], v[200:203], v[60:63]
	ds_read_b128 v[200:203], v246 offset:13312
	s_waitcnt lgkmcnt(3)
	v_mfma_f32_16x16x32_bf16 v[96:99], v[144:147], v[204:207], v[96:99]
	v_mfma_f32_16x16x32_bf16 v[104:107], v[148:151], v[204:207], v[104:107]
	v_mfma_f32_16x16x32_bf16 v[32:35], v[152:155], v[204:207], v[32:35]
	v_mfma_f32_16x16x32_bf16 v[40:43], v[156:159], v[204:207], v[40:43]
	ds_read_b128 v[204:207], v246 offset:14336
	s_waitcnt lgkmcnt(3)
	v_mfma_f32_16x16x32_bf16 v[100:103], v[144:147], v[242:245], v[100:103]
	v_mfma_f32_16x16x32_bf16 v[108:111], v[148:151], v[242:245], v[108:111]
	v_mfma_f32_16x16x32_bf16 v[36:39], v[152:155], v[242:245], v[36:39]
	v_mfma_f32_16x16x32_bf16 v[44:47], v[156:159], v[242:245], v[44:47]
	ds_read_b128 v[242:245], v246 offset:15360
	s_waitcnt lgkmcnt(3)
	v_mfma_f32_16x16x32_bf16 v[80:83], v[144:147], v[196:199], v[80:83]
	v_mfma_f32_16x16x32_bf16 v[88:91], v[148:151], v[196:199], v[88:91]
	v_mfma_f32_16x16x32_bf16 v[16:19], v[152:155], v[196:199], v[16:19]
	v_mfma_f32_16x16x32_bf16 v[24:27], v[156:159], v[196:199], v[24:27]
	s_waitcnt lgkmcnt(2)
	v_mfma_f32_16x16x32_bf16 v[84:87], v[144:147], v[200:203], v[84:87]
	v_mfma_f32_16x16x32_bf16 v[92:95], v[148:151], v[200:203], v[92:95]
	v_mfma_f32_16x16x32_bf16 v[20:23], v[152:155], v[200:203], v[20:23]
	v_mfma_f32_16x16x32_bf16 v[28:31], v[156:159], v[200:203], v[28:31]
	s_waitcnt lgkmcnt(1)
	v_mfma_f32_16x16x32_bf16 v[64:67], v[144:147], v[204:207], v[64:67]
	v_mfma_f32_16x16x32_bf16 v[72:75], v[148:151], v[204:207], v[72:75]
	v_mfma_f32_16x16x32_bf16 v[0:3], v[152:155], v[204:207], v[0:3]
	v_mfma_f32_16x16x32_bf16 v[8:11], v[156:159], v[204:207], v[8:11]
	s_waitcnt lgkmcnt(0)
	v_mfma_f32_16x16x32_bf16 v[68:71], v[144:147], v[242:245], v[68:71]
	v_mfma_f32_16x16x32_bf16 v[76:79], v[148:151], v[242:245], v[76:79]
	v_mfma_f32_16x16x32_bf16 v[4:7], v[152:155], v[242:245], v[4:7]
	v_mfma_f32_16x16x32_bf16 v[12:15], v[156:159], v[242:245], v[12:15]
	global_load_dwordx4 v[144:147], v[248:249], off
	global_load_dwordx4 v[148:151], v[248:249], off offset:256
	global_load_dwordx4 v[152:155], v[250:251], off
	global_load_dwordx4 v[156:159], v[250:251], off offset:256
	s_waitcnt vmcnt(10)
	s_barrier
	s_add_i32 s9, s8, 4
	s_lshl_b32 s96, s9, 13
	s_add_i32 m0, vcc_lo, 8192
	v_lshl_add_u64 v[160:161], v[188:189], 0, s[96:97]
	global_load_lds_dwordx4 v[160:161], off
	global_load_lds_dwordx4 v[160:161], off offset:1024
	ds_read_b128 v[196:199], v246 offset:16384
	ds_read_b128 v[200:203], v246 offset:17408
	ds_read_b128 v[204:207], v246 offset:18432
	ds_read_b128 v[242:245], v246 offset:19456
	s_add_i32 s9, s8, 4
	s_lshl_b32 s96, s9, 11
	v_lshl_add_u64 v[248:249], v[184:185], 0, s[96:97]
	v_lshl_add_u64 v[250:251], v[186:187], 0, s[96:97]
	s_waitcnt vmcnt(8) lgkmcnt(3)
	v_mfma_f32_16x16x32_bf16 v[112:115], v[128:131], v[196:199], v[112:115]
	v_mfma_f32_16x16x32_bf16 v[120:123], v[132:135], v[196:199], v[120:123]
	v_mfma_f32_16x16x32_bf16 v[48:51], v[136:139], v[196:199], v[48:51]
	v_mfma_f32_16x16x32_bf16 v[56:59], v[140:143], v[196:199], v[56:59]
	ds_read_b128 v[196:199], v246 offset:20480
	s_waitcnt lgkmcnt(3)
	v_mfma_f32_16x16x32_bf16 v[116:119], v[128:131], v[200:203], v[116:119]
	v_mfma_f32_16x16x32_bf16 v[124:127], v[132:135], v[200:203], v[124:127]
	v_mfma_f32_16x16x32_bf16 v[52:55], v[136:139], v[200:203], v[52:55]
	v_mfma_f32_16x16x32_bf16 v[60:63], v[140:143], v[200:203], v[60:63]
	ds_read_b128 v[200:203], v246 offset:21504
	s_waitcnt lgkmcnt(3)
	v_mfma_f32_16x16x32_bf16 v[96:99], v[128:131], v[204:207], v[96:99]
	v_mfma_f32_16x16x32_bf16 v[104:107], v[132:135], v[204:207], v[104:107]
	v_mfma_f32_16x16x32_bf16 v[32:35], v[136:139], v[204:207], v[32:35]
	v_mfma_f32_16x16x32_bf16 v[40:43], v[140:143], v[204:207], v[40:43]
	ds_read_b128 v[204:207], v246 offset:22528
	s_waitcnt lgkmcnt(3)
	v_mfma_f32_16x16x32_bf16 v[100:103], v[128:131], v[242:245], v[100:103]
	v_mfma_f32_16x16x32_bf16 v[108:111], v[132:135], v[242:245], v[108:111]
	v_mfma_f32_16x16x32_bf16 v[36:39], v[136:139], v[242:245], v[36:39]
	v_mfma_f32_16x16x32_bf16 v[44:47], v[140:143], v[242:245], v[44:47]
	ds_read_b128 v[242:245], v246 offset:23552
	s_waitcnt lgkmcnt(3)
	v_mfma_f32_16x16x32_bf16 v[80:83], v[128:131], v[196:199], v[80:83]
	v_mfma_f32_16x16x32_bf16 v[88:91], v[132:135], v[196:199], v[88:91]
	v_mfma_f32_16x16x32_bf16 v[16:19], v[136:139], v[196:199], v[16:19]
	v_mfma_f32_16x16x32_bf16 v[24:27], v[140:143], v[196:199], v[24:27]
	s_waitcnt lgkmcnt(2)
	v_mfma_f32_16x16x32_bf16 v[84:87], v[128:131], v[200:203], v[84:87]
	v_mfma_f32_16x16x32_bf16 v[92:95], v[132:135], v[200:203], v[92:95]
	v_mfma_f32_16x16x32_bf16 v[20:23], v[136:139], v[200:203], v[20:23]
	v_mfma_f32_16x16x32_bf16 v[28:31], v[140:143], v[200:203], v[28:31]
	s_waitcnt lgkmcnt(1)
	v_mfma_f32_16x16x32_bf16 v[64:67], v[128:131], v[204:207], v[64:67]
	v_mfma_f32_16x16x32_bf16 v[72:75], v[132:135], v[204:207], v[72:75]
	v_mfma_f32_16x16x32_bf16 v[0:3], v[136:139], v[204:207], v[0:3]
	v_mfma_f32_16x16x32_bf16 v[8:11], v[140:143], v[204:207], v[8:11]
	s_waitcnt lgkmcnt(0)
	v_mfma_f32_16x16x32_bf16 v[68:71], v[128:131], v[242:245], v[68:71]
	v_mfma_f32_16x16x32_bf16 v[76:79], v[132:135], v[242:245], v[76:79]
	v_mfma_f32_16x16x32_bf16 v[4:7], v[136:139], v[242:245], v[4:7]
	v_mfma_f32_16x16x32_bf16 v[12:15], v[140:143], v[242:245], v[12:15]
	global_load_dwordx4 v[128:131], v[248:249], off
	global_load_dwordx4 v[132:135], v[248:249], off offset:256
	global_load_dwordx4 v[136:139], v[250:251], off
	global_load_dwordx4 v[140:143], v[250:251], off offset:256
	s_waitcnt vmcnt(10)
	s_barrier
	s_add_i32 s9, s8, 5
	s_lshl_b32 s96, s9, 13
	s_add_i32 m0, vcc_lo, 16384
	v_lshl_add_u64 v[160:161], v[188:189], 0, s[96:97]
	global_load_lds_dwordx4 v[160:161], off
	global_load_lds_dwordx4 v[160:161], off offset:1024
	ds_read_b128 v[196:199], v246 offset:0
	ds_read_b128 v[200:203], v246 offset:1024
	ds_read_b128 v[204:207], v246 offset:2048
	ds_read_b128 v[242:245], v246 offset:3072
	s_add_i32 s9, s8, 5
	s_lshl_b32 s96, s9, 11
	v_lshl_add_u64 v[248:249], v[184:185], 0, s[96:97]
	v_lshl_add_u64 v[250:251], v[186:187], 0, s[96:97]
	s_waitcnt vmcnt(8) lgkmcnt(3)
	v_mfma_f32_16x16x32_bf16 v[112:115], v[144:147], v[196:199], v[112:115]
	v_mfma_f32_16x16x32_bf16 v[120:123], v[148:151], v[196:199], v[120:123]
	v_mfma_f32_16x16x32_bf16 v[48:51], v[152:155], v[196:199], v[48:51]
	v_mfma_f32_16x16x32_bf16 v[56:59], v[156:159], v[196:199], v[56:59]
	ds_read_b128 v[196:199], v246 offset:4096
	s_waitcnt lgkmcnt(3)
	v_mfma_f32_16x16x32_bf16 v[116:119], v[144:147], v[200:203], v[116:119]
	v_mfma_f32_16x16x32_bf16 v[124:127], v[148:151], v[200:203], v[124:127]
	v_mfma_f32_16x16x32_bf16 v[52:55], v[152:155], v[200:203], v[52:55]
	v_mfma_f32_16x16x32_bf16 v[60:63], v[156:159], v[200:203], v[60:63]
	ds_read_b128 v[200:203], v246 offset:5120
	s_waitcnt lgkmcnt(3)
	v_mfma_f32_16x16x32_bf16 v[96:99], v[144:147], v[204:207], v[96:99]
	v_mfma_f32_16x16x32_bf16 v[104:107], v[148:151], v[204:207], v[104:107]
	v_mfma_f32_16x16x32_bf16 v[32:35], v[152:155], v[204:207], v[32:35]
	v_mfma_f32_16x16x32_bf16 v[40:43], v[156:159], v[204:207], v[40:43]
	ds_read_b128 v[204:207], v246 offset:6144
	s_waitcnt lgkmcnt(3)
	v_mfma_f32_16x16x32_bf16 v[100:103], v[144:147], v[242:245], v[100:103]
	v_mfma_f32_16x16x32_bf16 v[108:111], v[148:151], v[242:245], v[108:111]
	v_mfma_f32_16x16x32_bf16 v[36:39], v[152:155], v[242:245], v[36:39]
	v_mfma_f32_16x16x32_bf16 v[44:47], v[156:159], v[242:245], v[44:47]
	ds_read_b128 v[242:245], v246 offset:7168
	s_waitcnt lgkmcnt(3)
	v_mfma_f32_16x16x32_bf16 v[80:83], v[144:147], v[196:199], v[80:83]
	v_mfma_f32_16x16x32_bf16 v[88:91], v[148:151], v[196:199], v[88:91]
	v_mfma_f32_16x16x32_bf16 v[16:19], v[152:155], v[196:199], v[16:19]
	v_mfma_f32_16x16x32_bf16 v[24:27], v[156:159], v[196:199], v[24:27]
	s_waitcnt lgkmcnt(2)
	v_mfma_f32_16x16x32_bf16 v[84:87], v[144:147], v[200:203], v[84:87]
	v_mfma_f32_16x16x32_bf16 v[92:95], v[148:151], v[200:203], v[92:95]
	v_mfma_f32_16x16x32_bf16 v[20:23], v[152:155], v[200:203], v[20:23]
	v_mfma_f32_16x16x32_bf16 v[28:31], v[156:159], v[200:203], v[28:31]
	s_waitcnt lgkmcnt(1)
	v_mfma_f32_16x16x32_bf16 v[64:67], v[144:147], v[204:207], v[64:67]
	v_mfma_f32_16x16x32_bf16 v[72:75], v[148:151], v[204:207], v[72:75]
	v_mfma_f32_16x16x32_bf16 v[0:3], v[152:155], v[204:207], v[0:3]
	v_mfma_f32_16x16x32_bf16 v[8:11], v[156:159], v[204:207], v[8:11]
	s_waitcnt lgkmcnt(0)
	v_mfma_f32_16x16x32_bf16 v[68:71], v[144:147], v[242:245], v[68:71]
	v_mfma_f32_16x16x32_bf16 v[76:79], v[148:151], v[242:245], v[76:79]
	v_mfma_f32_16x16x32_bf16 v[4:7], v[152:155], v[242:245], v[4:7]
	v_mfma_f32_16x16x32_bf16 v[12:15], v[156:159], v[242:245], v[12:15]
	global_load_dwordx4 v[144:147], v[248:249], off
	global_load_dwordx4 v[148:151], v[248:249], off offset:256
	global_load_dwordx4 v[152:155], v[250:251], off
	global_load_dwordx4 v[156:159], v[250:251], off offset:256
	s_waitcnt vmcnt(10)
	s_barrier
	s_add_i32 s9, s8, 6
	s_lshl_b32 s96, s9, 13
	s_mov_b32 m0, vcc_lo
	v_lshl_add_u64 v[160:161], v[188:189], 0, s[96:97]
	global_load_lds_dwordx4 v[160:161], off
	global_load_lds_dwordx4 v[160:161], off offset:1024
	ds_read_b128 v[196:199], v246 offset:8192
	ds_read_b128 v[200:203], v246 offset:9216
	ds_read_b128 v[204:207], v246 offset:10240
	ds_read_b128 v[242:245], v246 offset:11264
	s_add_i32 s9, s8, 6
	s_lshl_b32 s96, s9, 11
	v_lshl_add_u64 v[248:249], v[184:185], 0, s[96:97]
	v_lshl_add_u64 v[250:251], v[186:187], 0, s[96:97]
	s_waitcnt vmcnt(8) lgkmcnt(3)
	v_mfma_f32_16x16x32_bf16 v[112:115], v[128:131], v[196:199], v[112:115]
	v_mfma_f32_16x16x32_bf16 v[120:123], v[132:135], v[196:199], v[120:123]
	v_mfma_f32_16x16x32_bf16 v[48:51], v[136:139], v[196:199], v[48:51]
	v_mfma_f32_16x16x32_bf16 v[56:59], v[140:143], v[196:199], v[56:59]
	ds_read_b128 v[196:199], v246 offset:12288
	s_waitcnt lgkmcnt(3)
	v_mfma_f32_16x16x32_bf16 v[116:119], v[128:131], v[200:203], v[116:119]
	v_mfma_f32_16x16x32_bf16 v[124:127], v[132:135], v[200:203], v[124:127]
	v_mfma_f32_16x16x32_bf16 v[52:55], v[136:139], v[200:203], v[52:55]
	v_mfma_f32_16x16x32_bf16 v[60:63], v[140:143], v[200:203], v[60:63]
	ds_read_b128 v[200:203], v246 offset:13312
	s_waitcnt lgkmcnt(3)
	v_mfma_f32_16x16x32_bf16 v[96:99], v[128:131], v[204:207], v[96:99]
	v_mfma_f32_16x16x32_bf16 v[104:107], v[132:135], v[204:207], v[104:107]
	v_mfma_f32_16x16x32_bf16 v[32:35], v[136:139], v[204:207], v[32:35]
	v_mfma_f32_16x16x32_bf16 v[40:43], v[140:143], v[204:207], v[40:43]
	ds_read_b128 v[204:207], v246 offset:14336
	s_waitcnt lgkmcnt(3)
	v_mfma_f32_16x16x32_bf16 v[100:103], v[128:131], v[242:245], v[100:103]
	v_mfma_f32_16x16x32_bf16 v[108:111], v[132:135], v[242:245], v[108:111]
	v_mfma_f32_16x16x32_bf16 v[36:39], v[136:139], v[242:245], v[36:39]
	v_mfma_f32_16x16x32_bf16 v[44:47], v[140:143], v[242:245], v[44:47]
	ds_read_b128 v[242:245], v246 offset:15360
	s_waitcnt lgkmcnt(3)
	v_mfma_f32_16x16x32_bf16 v[80:83], v[128:131], v[196:199], v[80:83]
	v_mfma_f32_16x16x32_bf16 v[88:91], v[132:135], v[196:199], v[88:91]
	v_mfma_f32_16x16x32_bf16 v[16:19], v[136:139], v[196:199], v[16:19]
	v_mfma_f32_16x16x32_bf16 v[24:27], v[140:143], v[196:199], v[24:27]
	s_waitcnt lgkmcnt(2)
	v_mfma_f32_16x16x32_bf16 v[84:87], v[128:131], v[200:203], v[84:87]
	v_mfma_f32_16x16x32_bf16 v[92:95], v[132:135], v[200:203], v[92:95]
	v_mfma_f32_16x16x32_bf16 v[20:23], v[136:139], v[200:203], v[20:23]
	v_mfma_f32_16x16x32_bf16 v[28:31], v[140:143], v[200:203], v[28:31]
	s_waitcnt lgkmcnt(1)
	v_mfma_f32_16x16x32_bf16 v[64:67], v[128:131], v[204:207], v[64:67]
	v_mfma_f32_16x16x32_bf16 v[72:75], v[132:135], v[204:207], v[72:75]
	v_mfma_f32_16x16x32_bf16 v[0:3], v[136:139], v[204:207], v[0:3]
	v_mfma_f32_16x16x32_bf16 v[8:11], v[140:143], v[204:207], v[8:11]
	s_waitcnt lgkmcnt(0)
	v_mfma_f32_16x16x32_bf16 v[68:71], v[128:131], v[242:245], v[68:71]
	v_mfma_f32_16x16x32_bf16 v[76:79], v[132:135], v[242:245], v[76:79]
	v_mfma_f32_16x16x32_bf16 v[4:7], v[136:139], v[242:245], v[4:7]
	v_mfma_f32_16x16x32_bf16 v[12:15], v[140:143], v[242:245], v[12:15]
	global_load_dwordx4 v[128:131], v[248:249], off
	global_load_dwordx4 v[132:135], v[248:249], off offset:256
	global_load_dwordx4 v[136:139], v[250:251], off
	global_load_dwordx4 v[140:143], v[250:251], off offset:256
	s_waitcnt vmcnt(10)
	s_barrier
	s_add_i32 s9, s8, 7
	s_lshl_b32 s96, s9, 13
	s_add_i32 m0, vcc_lo, 8192
	v_lshl_add_u64 v[160:161], v[188:189], 0, s[96:97]
	global_load_lds_dwordx4 v[160:161], off
	global_load_lds_dwordx4 v[160:161], off offset:1024
	ds_read_b128 v[196:199], v246 offset:16384
	ds_read_b128 v[200:203], v246 offset:17408
	ds_read_b128 v[204:207], v246 offset:18432
	ds_read_b128 v[242:245], v246 offset:19456
	s_add_i32 s9, s8, 7
	s_lshl_b32 s96, s9, 11
	v_lshl_add_u64 v[248:249], v[184:185], 0, s[96:97]
	v_lshl_add_u64 v[250:251], v[186:187], 0, s[96:97]
	s_waitcnt vmcnt(8) lgkmcnt(3)
	v_mfma_f32_16x16x32_bf16 v[112:115], v[144:147], v[196:199], v[112:115]
	v_mfma_f32_16x16x32_bf16 v[120:123], v[148:151], v[196:199], v[120:123]
	v_mfma_f32_16x16x32_bf16 v[48:51], v[152:155], v[196:199], v[48:51]
	v_mfma_f32_16x16x32_bf16 v[56:59], v[156:159], v[196:199], v[56:59]
	ds_read_b128 v[196:199], v246 offset:20480
	s_waitcnt lgkmcnt(3)
	v_mfma_f32_16x16x32_bf16 v[116:119], v[144:147], v[200:203], v[116:119]
	v_mfma_f32_16x16x32_bf16 v[124:127], v[148:151], v[200:203], v[124:127]
	v_mfma_f32_16x16x32_bf16 v[52:55], v[152:155], v[200:203], v[52:55]
	v_mfma_f32_16x16x32_bf16 v[60:63], v[156:159], v[200:203], v[60:63]
	ds_read_b128 v[200:203], v246 offset:21504
	s_waitcnt lgkmcnt(3)
	v_mfma_f32_16x16x32_bf16 v[96:99], v[144:147], v[204:207], v[96:99]
	v_mfma_f32_16x16x32_bf16 v[104:107], v[148:151], v[204:207], v[104:107]
	v_mfma_f32_16x16x32_bf16 v[32:35], v[152:155], v[204:207], v[32:35]
	v_mfma_f32_16x16x32_bf16 v[40:43], v[156:159], v[204:207], v[40:43]
	ds_read_b128 v[204:207], v246 offset:22528
	s_waitcnt lgkmcnt(3)
	v_mfma_f32_16x16x32_bf16 v[100:103], v[144:147], v[242:245], v[100:103]
	v_mfma_f32_16x16x32_bf16 v[108:111], v[148:151], v[242:245], v[108:111]
	v_mfma_f32_16x16x32_bf16 v[36:39], v[152:155], v[242:245], v[36:39]
	v_mfma_f32_16x16x32_bf16 v[44:47], v[156:159], v[242:245], v[44:47]
	ds_read_b128 v[242:245], v246 offset:23552
	s_waitcnt lgkmcnt(3)
	v_mfma_f32_16x16x32_bf16 v[80:83], v[144:147], v[196:199], v[80:83]
	v_mfma_f32_16x16x32_bf16 v[88:91], v[148:151], v[196:199], v[88:91]
	v_mfma_f32_16x16x32_bf16 v[16:19], v[152:155], v[196:199], v[16:19]
	v_mfma_f32_16x16x32_bf16 v[24:27], v[156:159], v[196:199], v[24:27]
	s_waitcnt lgkmcnt(2)
	v_mfma_f32_16x16x32_bf16 v[84:87], v[144:147], v[200:203], v[84:87]
	v_mfma_f32_16x16x32_bf16 v[92:95], v[148:151], v[200:203], v[92:95]
	v_mfma_f32_16x16x32_bf16 v[20:23], v[152:155], v[200:203], v[20:23]
	v_mfma_f32_16x16x32_bf16 v[28:31], v[156:159], v[200:203], v[28:31]
	s_waitcnt lgkmcnt(1)
	v_mfma_f32_16x16x32_bf16 v[64:67], v[144:147], v[204:207], v[64:67]
	v_mfma_f32_16x16x32_bf16 v[72:75], v[148:151], v[204:207], v[72:75]
	v_mfma_f32_16x16x32_bf16 v[0:3], v[152:155], v[204:207], v[0:3]
	v_mfma_f32_16x16x32_bf16 v[8:11], v[156:159], v[204:207], v[8:11]
	s_waitcnt lgkmcnt(0)
	v_mfma_f32_16x16x32_bf16 v[68:71], v[144:147], v[242:245], v[68:71]
	v_mfma_f32_16x16x32_bf16 v[76:79], v[148:151], v[242:245], v[76:79]
	v_mfma_f32_16x16x32_bf16 v[4:7], v[152:155], v[242:245], v[4:7]
	v_mfma_f32_16x16x32_bf16 v[12:15], v[156:159], v[242:245], v[12:15]
	global_load_dwordx4 v[144:147], v[248:249], off
	global_load_dwordx4 v[148:151], v[248:249], off offset:256
	global_load_dwordx4 v[152:155], v[250:251], off
	global_load_dwordx4 v[156:159], v[250:251], off offset:256
	s_waitcnt vmcnt(10)
	s_barrier
	s_add_i32 s8, s8, 6
	s_cmp_lt_u32 s8, 84
	s_cbranch_scc1 .Lg16_down_k
	s_mov_b32 s96, 0xac000
	s_add_i32 m0, vcc_lo, 16384
	v_lshl_add_u64 v[160:161], v[188:189], 0, s[96:97]
	global_load_lds_dwordx4 v[160:161], off
	global_load_lds_dwordx4 v[160:161], off offset:1024
	ds_read_b128 v[196:199], v246 offset:0
	ds_read_b128 v[200:203], v246 offset:1024
	ds_read_b128 v[204:207], v246 offset:2048
	ds_read_b128 v[242:245], v246 offset:3072
	s_mov_b32 s96, 0x2b000
	v_lshl_add_u64 v[248:249], v[184:185], 0, s[96:97]
	v_lshl_add_u64 v[250:251], v[186:187], 0, s[96:97]
	s_waitcnt vmcnt(8) lgkmcnt(3)
	v_mfma_f32_16x16x32_bf16 v[112:115], v[128:131], v[196:199], v[112:115]
	v_mfma_f32_16x16x32_bf16 v[120:123], v[132:135], v[196:199], v[120:123]
	v_mfma_f32_16x16x32_bf16 v[48:51], v[136:139], v[196:199], v[48:51]
	v_mfma_f32_16x16x32_bf16 v[56:59], v[140:143], v[196:199], v[56:59]
	ds_read_b128 v[196:199], v246 offset:4096
	s_waitcnt lgkmcnt(3)
	v_mfma_f32_16x16x32_bf16 v[116:119], v[128:131], v[200:203], v[116:119]
	v_mfma_f32_16x16x32_bf16 v[124:127], v[132:135], v[200:203], v[124:127]
	v_mfma_f32_16x16x32_bf16 v[52:55], v[136:139], v[200:203], v[52:55]
	v_mfma_f32_16x16x32_bf16 v[60:63], v[140:143], v[200:203], v[60:63]
	ds_read_b128 v[200:203], v246 offset:5120
	s_waitcnt lgkmcnt(3)
	v_mfma_f32_16x16x32_bf16 v[96:99], v[128:131], v[204:207], v[96:99]
	v_mfma_f32_16x16x32_bf16 v[104:107], v[132:135], v[204:207], v[104:107]
	v_mfma_f32_16x16x32_bf16 v[32:35], v[136:139], v[204:207], v[32:35]
	v_mfma_f32_16x16x32_bf16 v[40:43], v[140:143], v[204:207], v[40:43]
	ds_read_b128 v[204:207], v246 offset:6144
	s_waitcnt lgkmcnt(3)
	v_mfma_f32_16x16x32_bf16 v[100:103], v[128:131], v[242:245], v[100:103]
	v_mfma_f32_16x16x32_bf16 v[108:111], v[132:135], v[242:245], v[108:111]
	v_mfma_f32_16x16x32_bf16 v[36:39], v[136:139], v[242:245], v[36:39]
	v_mfma_f32_16x16x32_bf16 v[44:47], v[140:143], v[242:245], v[44:47]
	ds_read_b128 v[242:245], v246 offset:7168
	s_waitcnt lgkmcnt(3)
	v_mfma_f32_16x16x32_bf16 v[80:83], v[128:131], v[196:199], v[80:83]
	v_mfma_f32_16x16x32_bf16 v[88:91], v[132:135], v[196:199], v[88:91]
	v_mfma_f32_16x16x32_bf16 v[16:19], v[136:139], v[196:199], v[16:19]
	v_mfma_f32_16x16x32_bf16 v[24:27], v[140:143], v[196:199], v[24:27]
	s_waitcnt lgkmcnt(2)
	v_mfma_f32_16x16x32_bf16 v[84:87], v[128:131], v[200:203], v[84:87]
	v_mfma_f32_16x16x32_bf16 v[92:95], v[132:135], v[200:203], v[92:95]
	v_mfma_f32_16x16x32_bf16 v[20:23], v[136:139], v[200:203], v[20:23]
	v_mfma_f32_16x16x32_bf16 v[28:31], v[140:143], v[200:203], v[28:31]
	s_waitcnt lgkmcnt(1)
	v_mfma_f32_16x16x32_bf16 v[64:67], v[128:131], v[204:207], v[64:67]
	v_mfma_f32_16x16x32_bf16 v[72:75], v[132:135], v[204:207], v[72:75]
	v_mfma_f32_16x16x32_bf16 v[0:3], v[136:139], v[204:207], v[0:3]
	v_mfma_f32_16x16x32_bf16 v[8:11], v[140:143], v[204:207], v[8:11]
	s_waitcnt lgkmcnt(0)
	v_mfma_f32_16x16x32_bf16 v[68:71], v[128:131], v[242:245], v[68:71]
	v_mfma_f32_16x16x32_bf16 v[76:79], v[132:135], v[242:245], v[76:79]
	v_mfma_f32_16x16x32_bf16 v[4:7], v[136:139], v[242:245], v[4:7]
	v_mfma_f32_16x16x32_bf16 v[12:15], v[140:143], v[242:245], v[12:15]
	global_load_dwordx4 v[128:131], v[248:249], off
	global_load_dwordx4 v[132:135], v[248:249], off offset:256
	global_load_dwordx4 v[136:139], v[250:251], off
	global_load_dwordx4 v[140:143], v[250:251], off offset:256
	s_waitcnt vmcnt(10)
	s_barrier
	s_mov_b32 s96, 0xae000
	s_mov_b32 m0, vcc_lo
	v_lshl_add_u64 v[160:161], v[188:189], 0, s[96:97]
	global_load_lds_dwordx4 v[160:161], off
	global_load_lds_dwordx4 v[160:161], off offset:1024
	ds_read_b128 v[196:199], v246 offset:8192
	ds_read_b128 v[200:203], v246 offset:9216
	ds_read_b128 v[204:207], v246 offset:10240
	ds_read_b128 v[242:245], v246 offset:11264
	s_mov_b32 s96, 0x2b800
	v_lshl_add_u64 v[248:249], v[184:185], 0, s[96:97]
	v_lshl_add_u64 v[250:251], v[186:187], 0, s[96:97]
	s_waitcnt vmcnt(8) lgkmcnt(3)
	v_mfma_f32_16x16x32_bf16 v[112:115], v[144:147], v[196:199], v[112:115]
	v_mfma_f32_16x16x32_bf16 v[120:123], v[148:151], v[196:199], v[120:123]
	v_mfma_f32_16x16x32_bf16 v[48:51], v[152:155], v[196:199], v[48:51]
	v_mfma_f32_16x16x32_bf16 v[56:59], v[156:159], v[196:199], v[56:59]
	ds_read_b128 v[196:199], v246 offset:12288
	s_waitcnt lgkmcnt(3)
	v_mfma_f32_16x16x32_bf16 v[116:119], v[144:147], v[200:203], v[116:119]
	v_mfma_f32_16x16x32_bf16 v[124:127], v[148:151], v[200:203], v[124:127]
	v_mfma_f32_16x16x32_bf16 v[52:55], v[152:155], v[200:203], v[52:55]
	v_mfma_f32_16x16x32_bf16 v[60:63], v[156:159], v[200:203], v[60:63]
	ds_read_b128 v[200:203], v246 offset:13312
	s_waitcnt lgkmcnt(3)
	v_mfma_f32_16x16x32_bf16 v[96:99], v[144:147], v[204:207], v[96:99]
	v_mfma_f32_16x16x32_bf16 v[104:107], v[148:151], v[204:207], v[104:107]
	v_mfma_f32_16x16x32_bf16 v[32:35], v[152:155], v[204:207], v[32:35]
	v_mfma_f32_16x16x32_bf16 v[40:43], v[156:159], v[204:207], v[40:43]
	ds_read_b128 v[204:207], v246 offset:14336
	s_waitcnt lgkmcnt(3)
	v_mfma_f32_16x16x32_bf16 v[100:103], v[144:147], v[242:245], v[100:103]
	v_mfma_f32_16x16x32_bf16 v[108:111], v[148:151], v[242:245], v[108:111]
	v_mfma_f32_16x16x32_bf16 v[36:39], v[152:155], v[242:245], v[36:39]
	v_mfma_f32_16x16x32_bf16 v[44:47], v[156:159], v[242:245], v[44:47]
	ds_read_b128 v[242:245], v246 offset:15360
	s_waitcnt lgkmcnt(3)
	v_mfma_f32_16x16x32_bf16 v[80:83], v[144:147], v[196:199], v[80:83]
	v_mfma_f32_16x16x32_bf16 v[88:91], v[148:151], v[196:199], v[88:91]
	v_mfma_f32_16x16x32_bf16 v[16:19], v[152:155], v[196:199], v[16:19]
	v_mfma_f32_16x16x32_bf16 v[24:27], v[156:159], v[196:199], v[24:27]
	s_waitcnt lgkmcnt(2)
	v_mfma_f32_16x16x32_bf16 v[84:87], v[144:147], v[200:203], v[84:87]
	v_mfma_f32_16x16x32_bf16 v[92:95], v[148:151], v[200:203], v[92:95]
	v_mfma_f32_16x16x32_bf16 v[20:23], v[152:155], v[200:203], v[20:23]
	v_mfma_f32_16x16x32_bf16 v[28:31], v[156:159], v[200:203], v[28:31]
	s_waitcnt lgkmcnt(1)
	v_mfma_f32_16x16x32_bf16 v[64:67], v[144:147], v[204:207], v[64:67]
	v_mfma_f32_16x16x32_bf16 v[72:75], v[148:151], v[204:207], v[72:75]
	v_mfma_f32_16x16x32_bf16 v[0:3], v[152:155], v[204:207], v[0:3]
	v_mfma_f32_16x16x32_bf16 v[8:11], v[156:159], v[204:207], v[8:11]
	s_waitcnt lgkmcnt(0)
	v_mfma_f32_16x16x32_bf16 v[68:71], v[144:147], v[242:245], v[68:71]
	v_mfma_f32_16x16x32_bf16 v[76:79], v[148:151], v[242:245], v[76:79]
	v_mfma_f32_16x16x32_bf16 v[4:7], v[152:155], v[242:245], v[4:7]
	v_mfma_f32_16x16x32_bf16 v[12:15], v[156:159], v[242:245], v[12:15]
	global_load_dwordx4 v[144:147], v[248:249], off
	global_load_dwordx4 v[148:151], v[248:249], off offset:256
	global_load_dwordx4 v[152:155], v[250:251], off
	global_load_dwordx4 v[156:159], v[250:251], off offset:256
	s_waitcnt vmcnt(10)
	s_barrier
	ds_read_b128 v[196:199], v246 offset:16384
	ds_read_b128 v[200:203], v246 offset:17408
	ds_read_b128 v[204:207], v246 offset:18432
	ds_read_b128 v[242:245], v246 offset:19456
	s_waitcnt vmcnt(6) lgkmcnt(3)
	v_mfma_f32_16x16x32_bf16 v[112:115], v[128:131], v[196:199], v[112:115]
	v_mfma_f32_16x16x32_bf16 v[120:123], v[132:135], v[196:199], v[120:123]
	v_mfma_f32_16x16x32_bf16 v[48:51], v[136:139], v[196:199], v[48:51]
	v_mfma_f32_16x16x32_bf16 v[56:59], v[140:143], v[196:199], v[56:59]
	ds_read_b128 v[196:199], v246 offset:20480
	s_waitcnt lgkmcnt(3)
	v_mfma_f32_16x16x32_bf16 v[116:119], v[128:131], v[200:203], v[116:119]
	v_mfma_f32_16x16x32_bf16 v[124:127], v[132:135], v[200:203], v[124:127]
	v_mfma_f32_16x16x32_bf16 v[52:55], v[136:139], v[200:203], v[52:55]
	v_mfma_f32_16x16x32_bf16 v[60:63], v[140:143], v[200:203], v[60:63]
	ds_read_b128 v[200:203], v246 offset:21504
	s_waitcnt lgkmcnt(3)
	v_mfma_f32_16x16x32_bf16 v[96:99], v[128:131], v[204:207], v[96:99]
	v_mfma_f32_16x16x32_bf16 v[104:107], v[132:135], v[204:207], v[104:107]
	v_mfma_f32_16x16x32_bf16 v[32:35], v[136:139], v[204:207], v[32:35]
	v_mfma_f32_16x16x32_bf16 v[40:43], v[140:143], v[204:207], v[40:43]
	ds_read_b128 v[204:207], v246 offset:22528
	s_waitcnt lgkmcnt(3)
	v_mfma_f32_16x16x32_bf16 v[100:103], v[128:131], v[242:245], v[100:103]
	v_mfma_f32_16x16x32_bf16 v[108:111], v[132:135], v[242:245], v[108:111]
	v_mfma_f32_16x16x32_bf16 v[36:39], v[136:139], v[242:245], v[36:39]
	v_mfma_f32_16x16x32_bf16 v[44:47], v[140:143], v[242:245], v[44:47]
	ds_read_b128 v[242:245], v246 offset:23552
	s_waitcnt lgkmcnt(3)
	v_mfma_f32_16x16x32_bf16 v[80:83], v[128:131], v[196:199], v[80:83]
	v_mfma_f32_16x16x32_bf16 v[88:91], v[132:135], v[196:199], v[88:91]
	v_mfma_f32_16x16x32_bf16 v[16:19], v[136:139], v[196:199], v[16:19]
	v_mfma_f32_16x16x32_bf16 v[24:27], v[140:143], v[196:199], v[24:27]
	s_waitcnt lgkmcnt(2)
	v_mfma_f32_16x16x32_bf16 v[84:87], v[128:131], v[200:203], v[84:87]
	v_mfma_f32_16x16x32_bf16 v[92:95], v[132:135], v[200:203], v[92:95]
	v_mfma_f32_16x16x32_bf16 v[20:23], v[136:139], v[200:203], v[20:23]
	v_mfma_f32_16x16x32_bf16 v[28:31], v[140:143], v[200:203], v[28:31]
	s_waitcnt lgkmcnt(1)
	v_mfma_f32_16x16x32_bf16 v[64:67], v[128:131], v[204:207], v[64:67]
	v_mfma_f32_16x16x32_bf16 v[72:75], v[132:135], v[204:207], v[72:75]
	v_mfma_f32_16x16x32_bf16 v[0:3], v[136:139], v[204:207], v[0:3]
	v_mfma_f32_16x16x32_bf16 v[8:11], v[140:143], v[204:207], v[8:11]
	s_waitcnt lgkmcnt(0)
	v_mfma_f32_16x16x32_bf16 v[68:71], v[128:131], v[242:245], v[68:71]
	v_mfma_f32_16x16x32_bf16 v[76:79], v[132:135], v[242:245], v[76:79]
	v_mfma_f32_16x16x32_bf16 v[4:7], v[136:139], v[242:245], v[4:7]
	v_mfma_f32_16x16x32_bf16 v[12:15], v[140:143], v[242:245], v[12:15]
	s_waitcnt vmcnt(4)
	s_barrier
	ds_read_b128 v[196:199], v246 offset:0
	ds_read_b128 v[200:203], v246 offset:1024
	ds_read_b128 v[204:207], v246 offset:2048
	ds_read_b128 v[242:245], v246 offset:3072
	s_waitcnt vmcnt(0) lgkmcnt(3)
	v_mfma_f32_16x16x32_bf16 v[112:115], v[144:147], v[196:199], v[112:115]
	v_mfma_f32_16x16x32_bf16 v[120:123], v[148:151], v[196:199], v[120:123]
	v_mfma_f32_16x16x32_bf16 v[48:51], v[152:155], v[196:199], v[48:51]
	v_mfma_f32_16x16x32_bf16 v[56:59], v[156:159], v[196:199], v[56:59]
	ds_read_b128 v[196:199], v246 offset:4096
	s_waitcnt lgkmcnt(3)
	v_mfma_f32_16x16x32_bf16 v[116:119], v[144:147], v[200:203], v[116:119]
	v_mfma_f32_16x16x32_bf16 v[124:127], v[148:151], v[200:203], v[124:127]
	v_mfma_f32_16x16x32_bf16 v[52:55], v[152:155], v[200:203], v[52:55]
	v_mfma_f32_16x16x32_bf16 v[60:63], v[156:159], v[200:203], v[60:63]
	ds_read_b128 v[200:203], v246 offset:5120
	s_waitcnt lgkmcnt(3)
	v_mfma_f32_16x16x32_bf16 v[96:99], v[144:147], v[204:207], v[96:99]
	v_mfma_f32_16x16x32_bf16 v[104:107], v[148:151], v[204:207], v[104:107]
	v_mfma_f32_16x16x32_bf16 v[32:35], v[152:155], v[204:207], v[32:35]
	v_mfma_f32_16x16x32_bf16 v[40:43], v[156:159], v[204:207], v[40:43]
	ds_read_b128 v[204:207], v246 offset:6144
	s_waitcnt lgkmcnt(3)
	v_mfma_f32_16x16x32_bf16 v[100:103], v[144:147], v[242:245], v[100:103]
	v_mfma_f32_16x16x32_bf16 v[108:111], v[148:151], v[242:245], v[108:111]
	v_mfma_f32_16x16x32_bf16 v[36:39], v[152:155], v[242:245], v[36:39]
	v_mfma_f32_16x16x32_bf16 v[44:47], v[156:159], v[242:245], v[44:47]
	ds_read_b128 v[242:245], v246 offset:7168
	v_permlane16_swap_b32_e32 v112, v116
	v_permlane16_swap_b32_e32 v113, v117
	v_permlane16_swap_b32_e32 v114, v118
	v_permlane16_swap_b32_e32 v115, v119
	v_permlane16_swap_b32_e32 v120, v124
	v_permlane16_swap_b32_e32 v121, v125
	v_permlane16_swap_b32_e32 v122, v126
	v_permlane16_swap_b32_e32 v123, v127
	v_permlane16_swap_b32_e32 v48, v52
	v_permlane16_swap_b32_e32 v49, v53
	v_permlane16_swap_b32_e32 v50, v54
	v_permlane16_swap_b32_e32 v51, v55
	v_permlane16_swap_b32_e32 v56, v60
	v_permlane16_swap_b32_e32 v57, v61
	v_permlane16_swap_b32_e32 v58, v62
	v_permlane16_swap_b32_e32 v59, v63
	v_permlane32_swap_b32_e32 v112, v116
	v_permlane32_swap_b32_e32 v113, v117
	v_permlane32_swap_b32_e32 v114, v118
	v_permlane32_swap_b32_e32 v115, v119
	v_permlane32_swap_b32_e32 v120, v124
	v_permlane32_swap_b32_e32 v121, v125
	v_permlane32_swap_b32_e32 v122, v126
	v_permlane32_swap_b32_e32 v123, v127
	v_permlane32_swap_b32_e32 v48, v52
	v_permlane32_swap_b32_e32 v49, v53
	v_permlane32_swap_b32_e32 v50, v54
	v_permlane32_swap_b32_e32 v51, v55
	v_permlane32_swap_b32_e32 v56, v60
	v_permlane32_swap_b32_e32 v57, v61
	v_permlane32_swap_b32_e32 v58, v62
	v_permlane32_swap_b32_e32 v59, v63
	s_waitcnt lgkmcnt(3)
	v_mfma_f32_16x16x32_bf16 v[80:83], v[144:147], v[196:199], v[80:83]
	v_mfma_f32_16x16x32_bf16 v[88:91], v[148:151], v[196:199], v[88:91]
	v_mfma_f32_16x16x32_bf16 v[16:19], v[152:155], v[196:199], v[16:19]
	v_mfma_f32_16x16x32_bf16 v[24:27], v[156:159], v[196:199], v[24:27]
	s_waitcnt lgkmcnt(2)
	v_mfma_f32_16x16x32_bf16 v[84:87], v[144:147], v[200:203], v[84:87]
	v_mfma_f32_16x16x32_bf16 v[92:95], v[148:151], v[200:203], v[92:95]
	v_mfma_f32_16x16x32_bf16 v[20:23], v[152:155], v[200:203], v[20:23]
	v_mfma_f32_16x16x32_bf16 v[28:31], v[156:159], v[200:203], v[28:31]
	v_permlane16_swap_b32_e32 v96, v100
	v_permlane16_swap_b32_e32 v97, v101
	v_permlane16_swap_b32_e32 v98, v102
	v_permlane16_swap_b32_e32 v99, v103
	v_permlane16_swap_b32_e32 v104, v108
	v_permlane16_swap_b32_e32 v105, v109
	v_permlane16_swap_b32_e32 v106, v110
	v_permlane16_swap_b32_e32 v107, v111
	v_permlane16_swap_b32_e32 v32, v36
	v_permlane16_swap_b32_e32 v33, v37
	v_permlane16_swap_b32_e32 v34, v38
	v_permlane16_swap_b32_e32 v35, v39
	v_permlane16_swap_b32_e32 v40, v44
	v_permlane16_swap_b32_e32 v41, v45
	v_permlane16_swap_b32_e32 v42, v46
	v_permlane16_swap_b32_e32 v43, v47
	v_permlane32_swap_b32_e32 v96, v100
	v_permlane32_swap_b32_e32 v97, v101
	v_permlane32_swap_b32_e32 v98, v102
	v_permlane32_swap_b32_e32 v99, v103
	v_permlane32_swap_b32_e32 v104, v108
	v_permlane32_swap_b32_e32 v105, v109
	v_permlane32_swap_b32_e32 v106, v110
	v_permlane32_swap_b32_e32 v107, v111
	v_permlane32_swap_b32_e32 v32, v36
	v_permlane32_swap_b32_e32 v33, v37
	v_permlane32_swap_b32_e32 v34, v38
	v_permlane32_swap_b32_e32 v35, v39
	v_permlane32_swap_b32_e32 v40, v44
	v_permlane32_swap_b32_e32 v41, v45
	v_permlane32_swap_b32_e32 v42, v46
	v_permlane32_swap_b32_e32 v43, v47
	s_waitcnt lgkmcnt(1)
	v_mfma_f32_16x16x32_bf16 v[64:67], v[144:147], v[204:207], v[64:67]
	v_mfma_f32_16x16x32_bf16 v[72:75], v[148:151], v[204:207], v[72:75]
	v_mfma_f32_16x16x32_bf16 v[0:3], v[152:155], v[204:207], v[0:3]
	v_mfma_f32_16x16x32_bf16 v[8:11], v[156:159], v[204:207], v[8:11]
	s_waitcnt lgkmcnt(0)
	v_mfma_f32_16x16x32_bf16 v[68:71], v[144:147], v[242:245], v[68:71]
	v_mfma_f32_16x16x32_bf16 v[76:79], v[148:151], v[242:245], v[76:79]
	v_mfma_f32_16x16x32_bf16 v[4:7], v[152:155], v[242:245], v[4:7]
	v_mfma_f32_16x16x32_bf16 v[12:15], v[156:159], v[242:245], v[12:15]
	v_permlane16_swap_b32_e32 v80, v84
	v_permlane16_swap_b32_e32 v81, v85
	v_permlane16_swap_b32_e32 v82, v86
	v_permlane16_swap_b32_e32 v83, v87
	v_permlane16_swap_b32_e32 v88, v92
	v_permlane16_swap_b32_e32 v89, v93
	v_permlane16_swap_b32_e32 v90, v94
	v_permlane16_swap_b32_e32 v91, v95
	v_permlane16_swap_b32_e32 v16, v20
	v_permlane16_swap_b32_e32 v17, v21
	v_permlane16_swap_b32_e32 v18, v22
	v_permlane16_swap_b32_e32 v19, v23
	v_permlane16_swap_b32_e32 v24, v28
	v_permlane16_swap_b32_e32 v25, v29
	v_permlane16_swap_b32_e32 v26, v30
	v_permlane16_swap_b32_e32 v27, v31
	v_permlane32_swap_b32_e32 v80, v84
	v_permlane32_swap_b32_e32 v81, v85
	v_permlane32_swap_b32_e32 v82, v86
	v_permlane32_swap_b32_e32 v83, v87
	v_permlane32_swap_b32_e32 v88, v92
	v_permlane32_swap_b32_e32 v89, v93
	v_permlane32_swap_b32_e32 v90, v94
	v_permlane32_swap_b32_e32 v91, v95
	v_permlane32_swap_b32_e32 v16, v20
	v_permlane32_swap_b32_e32 v17, v21
	v_permlane32_swap_b32_e32 v18, v22
	v_permlane32_swap_b32_e32 v19, v23
	v_permlane32_swap_b32_e32 v24, v28
	v_permlane32_swap_b32_e32 v25, v29
	v_permlane32_swap_b32_e32 v26, v30
	v_permlane32_swap_b32_e32 v27, v31
	s_barrier
	s_nop 7
	v_permlane16_swap_b32_e32 v64, v68
	v_permlane16_swap_b32_e32 v65, v69
	v_permlane16_swap_b32_e32 v66, v70
	v_permlane16_swap_b32_e32 v67, v71
	v_permlane16_swap_b32_e32 v72, v76
	v_permlane16_swap_b32_e32 v73, v77
	v_permlane16_swap_b32_e32 v74, v78
	v_permlane16_swap_b32_e32 v75, v79
	v_permlane16_swap_b32_e32 v0, v4
	v_permlane16_swap_b32_e32 v1, v5
	v_permlane16_swap_b32_e32 v2, v6
	v_permlane16_swap_b32_e32 v3, v7
	v_permlane16_swap_b32_e32 v8, v12
	v_permlane16_swap_b32_e32 v9, v13
	v_permlane16_swap_b32_e32 v10, v14
	v_permlane16_swap_b32_e32 v11, v15
	v_permlane32_swap_b32_e32 v64, v68
	v_permlane32_swap_b32_e32 v65, v69
	v_permlane32_swap_b32_e32 v66, v70
	v_permlane32_swap_b32_e32 v67, v71
	v_permlane32_swap_b32_e32 v72, v76
	v_permlane32_swap_b32_e32 v73, v77
	v_permlane32_swap_b32_e32 v74, v78
	v_permlane32_swap_b32_e32 v75, v79
	v_permlane32_swap_b32_e32 v0, v4
	v_permlane32_swap_b32_e32 v1, v5
	v_permlane32_swap_b32_e32 v2, v6
	v_permlane32_swap_b32_e32 v3, v7
	v_permlane32_swap_b32_e32 v8, v12
	v_permlane32_swap_b32_e32 v9, v13
	v_permlane32_swap_b32_e32 v10, v14
	v_permlane32_swap_b32_e32 v11, v15
	s_waitcnt vmcnt(0)
	s_waitcnt vmcnt(0)
	v_and_b32_e32 v188, 63, v179
	v_lshrrev_b32_e32 v189, 6, v179
	v_mul_u32_u24_e32 v249, 0x2400, v189
	v_mov_b32_e32 v250, v249
	v_lshrrev_b32_e32 v251, 5, v188
	v_mul_u32_u24_e32 v251, 0x440, v251
	v_add_u32_e32 v249, v249, v251
	v_and_b32_e32 v251, 31, v188
	v_lshl_add_u32 v249, v251, 2, v249
	v_lshrrev_b32_e32 v237, 4, v188
	v_mul_u32_u24_e32 v251, 0x110, v237
	v_add_u32_e32 v250, v250, v251
	v_and_b32_e32 v251, 15, v188
	v_lshlrev_b32_e32 v251, 4, v251
	v_add_u32_e32 v250, v250, v251
	v_lshl_add_u32 v237, v189, 6, v237
	v_lshl_add_u32 v237, v237, 12, v251
	v_add_u32_e32 v238, 16384, v237
	v_add_u32_e32 v239, 32768, v237
	v_add_u32_e32 v240, 49152, v237
	v_add_u32_e32 v241, 65536, v237
	v_add_u32_e32 v242, 81920, v237
	v_add_u32_e32 v243, 98304, v237
	v_add_u32_e32 v248, 114688, v237
	s_lshl_b32 s16, s7, 8
	s_lshl_b32 s18, s6, 9
	s_lshr_b32 s19, s7, 4
	v_readlane_b32 s12, v253, 46
	v_readlane_b32 s13, v253, 47
	v_readlane_b32 s14, v253, 46
	v_readlane_b32 s15, v253, 47
	s_add_i32 s17, s16, 0xffff8000
	s_cmpk_lt_u32 s7, 0x80
	s_cselect_b32 s12, s12, s62
	s_cselect_b32 s13, s13, s63
	s_cselect_b32 s14, s14, s62
	s_cselect_b32 s15, s15, s63
	s_cselect_b32 s19, s19, 8
	s_cselect_b32 s16, s16, s17
	s_mov_b32 s17, 0
	s_lshl_b64 s[16:17], s[16:17], 12
	s_add_u32 s16, s16, s18
	s_addc_u32 s17, s17, 0
	s_add_u32 s12, s12, s16
	s_addc_u32 s13, s13, s17
	s_add_u32 s14, s14, s16
	s_addc_u32 s15, s15, s17
	s_mul_i32 s19, s19, 0x6000
	s_add_u32 s20, s0, s19
	s_addc_u32 s21, s1, 0
	s_add_u32 s20, s20, s18
	s_addc_u32 s21, s21, 0
	global_load_dwordx4 v[244:247], v251, s[20:21]
	global_load_dwordx4 v[160:163], v237, s[12:13]
	global_load_dwordx4 v[164:167], v238, s[12:13]
	global_load_dwordx4 v[168:171], v239, s[12:13]
	global_load_dwordx4 v[172:175], v240, s[12:13]
	global_load_dwordx4 v[196:199], v241, s[12:13]
	global_load_dwordx4 v[200:203], v242, s[12:13]
	global_load_dwordx4 v[204:207], v243, s[12:13]
	global_load_dwordx4 v[184:187], v248, s[12:13]
	ds_write_b32 v249, v112
	ds_write_b32 v249, v113 offset:272
	ds_write_b32 v249, v114 offset:544
	ds_write_b32 v249, v115 offset:816
	ds_write_b32 v249, v116 offset:2176
	ds_write_b32 v249, v117 offset:2448
	ds_write_b32 v249, v118 offset:2720
	ds_write_b32 v249, v119 offset:2992
	ds_write_b32 v249, v120 offset:4352
	ds_write_b32 v249, v121 offset:4624
	ds_write_b32 v249, v122 offset:4896
	ds_write_b32 v249, v123 offset:5168
	ds_write_b32 v249, v124 offset:6528
	ds_write_b32 v249, v125 offset:6800
	ds_write_b32 v249, v126 offset:7072
	ds_write_b32 v249, v127 offset:7344
	ds_write_b32 v249, v96 offset:128
	ds_write_b32 v249, v97 offset:400
	ds_write_b32 v249, v98 offset:672
	ds_write_b32 v249, v99 offset:944
	ds_write_b32 v249, v100 offset:2304
	ds_write_b32 v249, v101 offset:2576
	ds_write_b32 v249, v102 offset:2848
	ds_write_b32 v249, v103 offset:3120
	ds_write_b32 v249, v104 offset:4480
	ds_write_b32 v249, v105 offset:4752
	ds_write_b32 v249, v106 offset:5024
	ds_write_b32 v249, v107 offset:5296
	ds_write_b32 v249, v108 offset:6656
	ds_write_b32 v249, v109 offset:6928
	ds_write_b32 v249, v110 offset:7200
	ds_write_b32 v249, v111 offset:7472
	s_waitcnt lgkmcnt(0)
	ds_read_b128 v[128:131], v250
	ds_read_b128 v[132:135], v250 offset:1088
	ds_read_b128 v[136:139], v250 offset:2176
	ds_read_b128 v[140:143], v250 offset:3264
	ds_read_b128 v[144:147], v250 offset:4352
	ds_read_b128 v[148:151], v250 offset:5440
	ds_read_b128 v[152:155], v250 offset:6528
	ds_read_b128 v[156:159], v250 offset:7616
	s_waitcnt vmcnt(7) lgkmcnt(7)
	v_fma_f32 v128, v244, v128, v160
	v_fma_f32 v129, v245, v129, v161
	v_fma_f32 v130, v246, v130, v162
	v_fma_f32 v131, v247, v131, v163
	global_store_dwordx4 v237, v[128:131], s[14:15]
	s_waitcnt vmcnt(7) lgkmcnt(6)
	v_fma_f32 v132, v244, v132, v164
	v_fma_f32 v133, v245, v133, v165
	v_fma_f32 v134, v246, v134, v166
	v_fma_f32 v135, v247, v135, v167
	global_store_dwordx4 v238, v[132:135], s[14:15]
	s_waitcnt vmcnt(7) lgkmcnt(5)
	v_fma_f32 v136, v244, v136, v168
	v_fma_f32 v137, v245, v137, v169
	v_fma_f32 v138, v246, v138, v170
	v_fma_f32 v139, v247, v139, v171
	global_store_dwordx4 v239, v[136:139], s[14:15]
	s_waitcnt vmcnt(7) lgkmcnt(4)
	v_fma_f32 v140, v244, v140, v172
	v_fma_f32 v141, v245, v141, v173
	v_fma_f32 v142, v246, v142, v174
	v_fma_f32 v143, v247, v143, v175
	global_store_dwordx4 v240, v[140:143], s[14:15]
	s_waitcnt vmcnt(7) lgkmcnt(3)
	v_fma_f32 v144, v244, v144, v196
	v_fma_f32 v145, v245, v145, v197
	v_fma_f32 v146, v246, v146, v198
	v_fma_f32 v147, v247, v147, v199
	global_store_dwordx4 v241, v[144:147], s[14:15]
	s_waitcnt vmcnt(7) lgkmcnt(2)
	v_fma_f32 v148, v244, v148, v200
	v_fma_f32 v149, v245, v149, v201
	v_fma_f32 v150, v246, v150, v202
	v_fma_f32 v151, v247, v151, v203
	global_store_dwordx4 v242, v[148:151], s[14:15]
	s_waitcnt vmcnt(7) lgkmcnt(1)
	v_fma_f32 v152, v244, v152, v204
	v_fma_f32 v153, v245, v153, v205
	v_fma_f32 v154, v246, v154, v206
	v_fma_f32 v155, v247, v155, v207
	global_store_dwordx4 v243, v[152:155], s[14:15]
	s_waitcnt vmcnt(7) lgkmcnt(0)
	v_fma_f32 v156, v244, v156, v184
	v_fma_f32 v157, v245, v157, v185
	v_fma_f32 v158, v246, v158, v186
	v_fma_f32 v159, v247, v159, v187
	global_store_dwordx4 v248, v[156:159], s[14:15]
	global_load_dwordx4 v[244:247], v251, s[20:21] offset:256
	global_load_dwordx4 v[160:163], v237, s[12:13] offset:256
	global_load_dwordx4 v[164:167], v238, s[12:13] offset:256
	global_load_dwordx4 v[168:171], v239, s[12:13] offset:256
	global_load_dwordx4 v[172:175], v240, s[12:13] offset:256
	global_load_dwordx4 v[196:199], v241, s[12:13] offset:256
	global_load_dwordx4 v[200:203], v242, s[12:13] offset:256
	global_load_dwordx4 v[204:207], v243, s[12:13] offset:256
	global_load_dwordx4 v[184:187], v248, s[12:13] offset:256
	ds_write_b32 v249, v80
	ds_write_b32 v249, v81 offset:272
	ds_write_b32 v249, v82 offset:544
	ds_write_b32 v249, v83 offset:816
	ds_write_b32 v249, v84 offset:2176
	ds_write_b32 v249, v85 offset:2448
	ds_write_b32 v249, v86 offset:2720
	ds_write_b32 v249, v87 offset:2992
	ds_write_b32 v249, v88 offset:4352
	ds_write_b32 v249, v89 offset:4624
	ds_write_b32 v249, v90 offset:4896
	ds_write_b32 v249, v91 offset:5168
	ds_write_b32 v249, v92 offset:6528
	ds_write_b32 v249, v93 offset:6800
	ds_write_b32 v249, v94 offset:7072
	ds_write_b32 v249, v95 offset:7344
	ds_write_b32 v249, v64 offset:128
	ds_write_b32 v249, v65 offset:400
	ds_write_b32 v249, v66 offset:672
	ds_write_b32 v249, v67 offset:944
	ds_write_b32 v249, v68 offset:2304
	ds_write_b32 v249, v69 offset:2576
	ds_write_b32 v249, v70 offset:2848
	ds_write_b32 v249, v71 offset:3120
	ds_write_b32 v249, v72 offset:4480
	ds_write_b32 v249, v73 offset:4752
	ds_write_b32 v249, v74 offset:5024
	ds_write_b32 v249, v75 offset:5296
	ds_write_b32 v249, v76 offset:6656
	ds_write_b32 v249, v77 offset:6928
	ds_write_b32 v249, v78 offset:7200
	ds_write_b32 v249, v79 offset:7472
	s_waitcnt lgkmcnt(0)
	ds_read_b128 v[128:131], v250
	ds_read_b128 v[132:135], v250 offset:1088
	ds_read_b128 v[136:139], v250 offset:2176
	ds_read_b128 v[140:143], v250 offset:3264
	ds_read_b128 v[144:147], v250 offset:4352
	ds_read_b128 v[148:151], v250 offset:5440
	ds_read_b128 v[152:155], v250 offset:6528
	ds_read_b128 v[156:159], v250 offset:7616
	s_waitcnt vmcnt(7) lgkmcnt(7)
	v_fma_f32 v128, v244, v128, v160
	v_fma_f32 v129, v245, v129, v161
	v_fma_f32 v130, v246, v130, v162
	v_fma_f32 v131, v247, v131, v163
	global_store_dwordx4 v237, v[128:131], s[14:15] offset:256
	s_waitcnt vmcnt(7) lgkmcnt(6)
	v_fma_f32 v132, v244, v132, v164
	v_fma_f32 v133, v245, v133, v165
	v_fma_f32 v134, v246, v134, v166
	v_fma_f32 v135, v247, v135, v167
	global_store_dwordx4 v238, v[132:135], s[14:15] offset:256
	s_waitcnt vmcnt(7) lgkmcnt(5)
	v_fma_f32 v136, v244, v136, v168
	v_fma_f32 v137, v245, v137, v169
	v_fma_f32 v138, v246, v138, v170
	v_fma_f32 v139, v247, v139, v171
	global_store_dwordx4 v239, v[136:139], s[14:15] offset:256
	s_waitcnt vmcnt(7) lgkmcnt(4)
	v_fma_f32 v140, v244, v140, v172
	v_fma_f32 v141, v245, v141, v173
	v_fma_f32 v142, v246, v142, v174
	v_fma_f32 v143, v247, v143, v175
	global_store_dwordx4 v240, v[140:143], s[14:15] offset:256
	s_waitcnt vmcnt(7) lgkmcnt(3)
	v_fma_f32 v144, v244, v144, v196
	v_fma_f32 v145, v245, v145, v197
	v_fma_f32 v146, v246, v146, v198
	v_fma_f32 v147, v247, v147, v199
	global_store_dwordx4 v241, v[144:147], s[14:15] offset:256
	s_waitcnt vmcnt(7) lgkmcnt(2)
	v_fma_f32 v148, v244, v148, v200
	v_fma_f32 v149, v245, v149, v201
	v_fma_f32 v150, v246, v150, v202
	v_fma_f32 v151, v247, v151, v203
	global_store_dwordx4 v242, v[148:151], s[14:15] offset:256
	s_waitcnt vmcnt(7) lgkmcnt(1)
	v_fma_f32 v152, v244, v152, v204
	v_fma_f32 v153, v245, v153, v205
	v_fma_f32 v154, v246, v154, v206
	v_fma_f32 v155, v247, v155, v207
	global_store_dwordx4 v243, v[152:155], s[14:15] offset:256
	s_waitcnt vmcnt(7) lgkmcnt(0)
	v_fma_f32 v156, v244, v156, v184
	v_fma_f32 v157, v245, v157, v185
	v_fma_f32 v158, v246, v158, v186
	v_fma_f32 v159, v247, v159, v187
	global_store_dwordx4 v248, v[156:159], s[14:15] offset:256
	s_add_u32 s12, s12, 0x20000
	s_addc_u32 s13, s13, 0
	s_add_u32 s14, s14, 0x20000
	s_addc_u32 s15, s15, 0
	global_load_dwordx4 v[244:247], v251, s[20:21]
	global_load_dwordx4 v[160:163], v237, s[12:13]
	global_load_dwordx4 v[164:167], v238, s[12:13]
	global_load_dwordx4 v[168:171], v239, s[12:13]
	global_load_dwordx4 v[172:175], v240, s[12:13]
	global_load_dwordx4 v[196:199], v241, s[12:13]
	global_load_dwordx4 v[200:203], v242, s[12:13]
	global_load_dwordx4 v[204:207], v243, s[12:13]
	global_load_dwordx4 v[184:187], v248, s[12:13]
	ds_write_b32 v249, v48
	ds_write_b32 v249, v49 offset:272
	ds_write_b32 v249, v50 offset:544
	ds_write_b32 v249, v51 offset:816
	ds_write_b32 v249, v52 offset:2176
	ds_write_b32 v249, v53 offset:2448
	ds_write_b32 v249, v54 offset:2720
	ds_write_b32 v249, v55 offset:2992
	ds_write_b32 v249, v56 offset:4352
	ds_write_b32 v249, v57 offset:4624
	ds_write_b32 v249, v58 offset:4896
	ds_write_b32 v249, v59 offset:5168
	ds_write_b32 v249, v60 offset:6528
	ds_write_b32 v249, v61 offset:6800
	ds_write_b32 v249, v62 offset:7072
	ds_write_b32 v249, v63 offset:7344
	ds_write_b32 v249, v32 offset:128
	ds_write_b32 v249, v33 offset:400
	ds_write_b32 v249, v34 offset:672
	ds_write_b32 v249, v35 offset:944
	ds_write_b32 v249, v36 offset:2304
	ds_write_b32 v249, v37 offset:2576
	ds_write_b32 v249, v38 offset:2848
	ds_write_b32 v249, v39 offset:3120
	ds_write_b32 v249, v40 offset:4480
	ds_write_b32 v249, v41 offset:4752
	ds_write_b32 v249, v42 offset:5024
	ds_write_b32 v249, v43 offset:5296
	ds_write_b32 v249, v44 offset:6656
	ds_write_b32 v249, v45 offset:6928
	ds_write_b32 v249, v46 offset:7200
	ds_write_b32 v249, v47 offset:7472
	s_waitcnt lgkmcnt(0)
	ds_read_b128 v[128:131], v250
	ds_read_b128 v[132:135], v250 offset:1088
	ds_read_b128 v[136:139], v250 offset:2176
	ds_read_b128 v[140:143], v250 offset:3264
	ds_read_b128 v[144:147], v250 offset:4352
	ds_read_b128 v[148:151], v250 offset:5440
	ds_read_b128 v[152:155], v250 offset:6528
	ds_read_b128 v[156:159], v250 offset:7616
	s_waitcnt vmcnt(7) lgkmcnt(7)
	v_fma_f32 v128, v244, v128, v160
	v_fma_f32 v129, v245, v129, v161
	v_fma_f32 v130, v246, v130, v162
	v_fma_f32 v131, v247, v131, v163
	global_store_dwordx4 v237, v[128:131], s[14:15]
	s_waitcnt vmcnt(7) lgkmcnt(6)
	v_fma_f32 v132, v244, v132, v164
	v_fma_f32 v133, v245, v133, v165
	v_fma_f32 v134, v246, v134, v166
	v_fma_f32 v135, v247, v135, v167
	global_store_dwordx4 v238, v[132:135], s[14:15]
	s_waitcnt vmcnt(7) lgkmcnt(5)
	v_fma_f32 v136, v244, v136, v168
	v_fma_f32 v137, v245, v137, v169
	v_fma_f32 v138, v246, v138, v170
	v_fma_f32 v139, v247, v139, v171
	global_store_dwordx4 v239, v[136:139], s[14:15]
	s_waitcnt vmcnt(7) lgkmcnt(4)
	v_fma_f32 v140, v244, v140, v172
	v_fma_f32 v141, v245, v141, v173
	v_fma_f32 v142, v246, v142, v174
	v_fma_f32 v143, v247, v143, v175
	global_store_dwordx4 v240, v[140:143], s[14:15]
	s_waitcnt vmcnt(7) lgkmcnt(3)
	v_fma_f32 v144, v244, v144, v196
	v_fma_f32 v145, v245, v145, v197
	v_fma_f32 v146, v246, v146, v198
	v_fma_f32 v147, v247, v147, v199
	global_store_dwordx4 v241, v[144:147], s[14:15]
	s_waitcnt vmcnt(7) lgkmcnt(2)
	v_fma_f32 v148, v244, v148, v200
	v_fma_f32 v149, v245, v149, v201
	v_fma_f32 v150, v246, v150, v202
	v_fma_f32 v151, v247, v151, v203
	global_store_dwordx4 v242, v[148:151], s[14:15]
	s_waitcnt vmcnt(7) lgkmcnt(1)
	v_fma_f32 v152, v244, v152, v204
	v_fma_f32 v153, v245, v153, v205
	v_fma_f32 v154, v246, v154, v206
	v_fma_f32 v155, v247, v155, v207
	global_store_dwordx4 v243, v[152:155], s[14:15]
	s_waitcnt vmcnt(7) lgkmcnt(0)
	v_fma_f32 v156, v244, v156, v184
	v_fma_f32 v157, v245, v157, v185
	v_fma_f32 v158, v246, v158, v186
	v_fma_f32 v159, v247, v159, v187
	global_store_dwordx4 v248, v[156:159], s[14:15]
	global_load_dwordx4 v[244:247], v251, s[20:21] offset:256
	global_load_dwordx4 v[160:163], v237, s[12:13] offset:256
	global_load_dwordx4 v[164:167], v238, s[12:13] offset:256
	global_load_dwordx4 v[168:171], v239, s[12:13] offset:256
	global_load_dwordx4 v[172:175], v240, s[12:13] offset:256
	global_load_dwordx4 v[196:199], v241, s[12:13] offset:256
	global_load_dwordx4 v[200:203], v242, s[12:13] offset:256
	global_load_dwordx4 v[204:207], v243, s[12:13] offset:256
	global_load_dwordx4 v[184:187], v248, s[12:13] offset:256
	ds_write_b32 v249, v16
	ds_write_b32 v249, v17 offset:272
	ds_write_b32 v249, v18 offset:544
	ds_write_b32 v249, v19 offset:816
	ds_write_b32 v249, v20 offset:2176
	ds_write_b32 v249, v21 offset:2448
	ds_write_b32 v249, v22 offset:2720
	ds_write_b32 v249, v23 offset:2992
	ds_write_b32 v249, v24 offset:4352
	ds_write_b32 v249, v25 offset:4624
	ds_write_b32 v249, v26 offset:4896
	ds_write_b32 v249, v27 offset:5168
	ds_write_b32 v249, v28 offset:6528
	ds_write_b32 v249, v29 offset:6800
	ds_write_b32 v249, v30 offset:7072
	ds_write_b32 v249, v31 offset:7344
	ds_write_b32 v249, v0 offset:128
	ds_write_b32 v249, v1 offset:400
	ds_write_b32 v249, v2 offset:672
	ds_write_b32 v249, v3 offset:944
	ds_write_b32 v249, v4 offset:2304
	ds_write_b32 v249, v5 offset:2576
	ds_write_b32 v249, v6 offset:2848
	ds_write_b32 v249, v7 offset:3120
	ds_write_b32 v249, v8 offset:4480
	ds_write_b32 v249, v9 offset:4752
	ds_write_b32 v249, v10 offset:5024
	ds_write_b32 v249, v11 offset:5296
	ds_write_b32 v249, v12 offset:6656
	ds_write_b32 v249, v13 offset:6928
	ds_write_b32 v249, v14 offset:7200
	ds_write_b32 v249, v15 offset:7472
	s_waitcnt lgkmcnt(0)
	ds_read_b128 v[128:131], v250
	ds_read_b128 v[132:135], v250 offset:1088
	ds_read_b128 v[136:139], v250 offset:2176
	ds_read_b128 v[140:143], v250 offset:3264
	ds_read_b128 v[144:147], v250 offset:4352
	ds_read_b128 v[148:151], v250 offset:5440
	ds_read_b128 v[152:155], v250 offset:6528
	ds_read_b128 v[156:159], v250 offset:7616
	s_waitcnt vmcnt(7) lgkmcnt(7)
	v_fma_f32 v128, v244, v128, v160
	v_fma_f32 v129, v245, v129, v161
	v_fma_f32 v130, v246, v130, v162
	v_fma_f32 v131, v247, v131, v163
	global_store_dwordx4 v237, v[128:131], s[14:15] offset:256
	s_waitcnt vmcnt(7) lgkmcnt(6)
	v_fma_f32 v132, v244, v132, v164
	v_fma_f32 v133, v245, v133, v165
	v_fma_f32 v134, v246, v134, v166
	v_fma_f32 v135, v247, v135, v167
	global_store_dwordx4 v238, v[132:135], s[14:15] offset:256
	s_waitcnt vmcnt(7) lgkmcnt(5)
	v_fma_f32 v136, v244, v136, v168
	v_fma_f32 v137, v245, v137, v169
	v_fma_f32 v138, v246, v138, v170
	v_fma_f32 v139, v247, v139, v171
	global_store_dwordx4 v239, v[136:139], s[14:15] offset:256
	s_waitcnt vmcnt(7) lgkmcnt(4)
	v_fma_f32 v140, v244, v140, v172
	v_fma_f32 v141, v245, v141, v173
	v_fma_f32 v142, v246, v142, v174
	v_fma_f32 v143, v247, v143, v175
	global_store_dwordx4 v240, v[140:143], s[14:15] offset:256
	s_waitcnt vmcnt(7) lgkmcnt(3)
	v_fma_f32 v144, v244, v144, v196
	v_fma_f32 v145, v245, v145, v197
	v_fma_f32 v146, v246, v146, v198
	v_fma_f32 v147, v247, v147, v199
	global_store_dwordx4 v241, v[144:147], s[14:15] offset:256
	s_waitcnt vmcnt(7) lgkmcnt(2)
	v_fma_f32 v148, v244, v148, v200
	v_fma_f32 v149, v245, v149, v201
	v_fma_f32 v150, v246, v150, v202
	v_fma_f32 v151, v247, v151, v203
	global_store_dwordx4 v242, v[148:151], s[14:15] offset:256
	s_waitcnt vmcnt(7) lgkmcnt(1)
	v_fma_f32 v152, v244, v152, v204
	v_fma_f32 v153, v245, v153, v205
	v_fma_f32 v154, v246, v154, v206
	v_fma_f32 v155, v247, v155, v207
	global_store_dwordx4 v243, v[152:155], s[14:15] offset:256
	s_waitcnt vmcnt(7) lgkmcnt(0)
	v_fma_f32 v156, v244, v156, v184
	v_fma_f32 v157, v245, v157, v185
	v_fma_f32 v158, v246, v158, v186
	v_fma_f32 v159, v247, v159, v187
	global_store_dwordx4 v248, v[156:159], s[14:15] offset:256
	s_waitcnt lgkmcnt(0)
	v_readlane_b32 s8, v254, 11
	s_add_i32 s2, s2, s8
	s_cmp_lt_i32 s2, s26
	s_barrier
	s_cbranch_scc1 .LBB0_1086
